# mixer pooling scan: fewer VALU per element (d16_hi reads, cvt_pk, hoisted reciprocal, batched LDS reads) + skip final barrier
# speedup vs baseline: 1.0120x; 1.0061x over previous
.LBB0_782:
	s_or_b64 exec, exec, s[0:1]
	s_lshr_b32 s0, s16, 3
	s_and_b32 s0, s0, 1
	s_lshl_b32 s0, s0, 6
	s_lshl_b32 s1, s6, 7
	v_lshlrev_b32_e32 v2, 10, v0
	s_or_b32 s0, s1, s0
	v_sub_u32_e32 v2, 0, v2
	s_and_b32 s0, s0, 0x7c0
	s_mov_b32 s1, 0
	s_add_i32 s6, 0, 0x3c00
	v_add_u32_e32 v2, 0x4000, v2
	s_mov_b32 s7, 0
	v_cvt_f32_i32_e32 v34, v0
	v_rcp_iflag_f32_e32 v34, v34
	v_mov_b32_e32 v10, 0
	v_mov_b32_e32 v11, 0
	v_mov_b32_e32 v12, 0
	v_mov_b32_e32 v13, 0
	v_mov_b32_e32 v14, 0
	v_mov_b32_e32 v15, 0
	v_mov_b32_e32 v16, 0
	v_mov_b32_e32 v17, 0
	v_mov_b32_e32 v18, 0
	v_mov_b32_e32 v19, 0
	v_mov_b32_e32 v20, 0
	v_mov_b32_e32 v21, 0
	v_mov_b32_e32 v22, 0
	v_mov_b32_e32 v23, 0
	v_mov_b32_e32 v24, 0
	v_mov_b32_e32 v25, 0
.LBB0_783:
	s_add_i32 s8, s0, s7
	v_add_u32_e32 v4, s6, v1
	v_add_u32_e32 v5, v2, v1
	ds_read_u16_d16_hi v10, v4
	ds_read_u16_d16_hi v11, v5
	ds_read_u16_d16_hi v12, v4 offset:1024
	ds_read_u16_d16_hi v13, v5 offset:1024
	ds_read_u16_d16_hi v14, v4 offset:2048
	ds_read_u16_d16_hi v15, v5 offset:2048
	ds_read_u16_d16_hi v16, v4 offset:3072
	ds_read_u16_d16_hi v17, v5 offset:3072
	ds_read_u16_d16_hi v18, v4 offset:4096
	ds_read_u16_d16_hi v19, v5 offset:4096
	ds_read_u16_d16_hi v20, v4 offset:5120
	ds_read_u16_d16_hi v21, v5 offset:5120
	ds_read_u16_d16_hi v22, v4 offset:6144
	ds_read_u16_d16_hi v23, v5 offset:6144
	ds_read_u16_d16_hi v24, v4 offset:7168
	ds_read_u16_d16_hi v25, v5 offset:7168
	v_add_u32_e32 v6, s1, v1
	v_add_u32_e32 v7, 0x13c00, v6
	v_add_u32_e32 v2, 0x2000, v2
	s_cmp_lt_i32 s8, 16
	s_cbranch_scc1 .Lscan_slow
	s_add_i32 s7, s7, 8
	s_addk_i32 s6, 0x2000
	s_addk_i32 s1, 0x2080
	s_waitcnt lgkmcnt(0)
	v_add_f32_e32 v3, v3, v10
	v_fma_f32 v8, v34, v3, -v10
	v_cvt_pk_bf16_f32 v9, v8, v8
	ds_write_b16 v7, v9
	v_sub_f32_e32 v3, v3, v11
	v_add_f32_e32 v3, v3, v12
	v_fma_f32 v8, v34, v3, -v12
	v_cvt_pk_bf16_f32 v9, v8, v8
	ds_write_b16 v7, v9 offset:1040
	v_sub_f32_e32 v3, v3, v13
	v_add_f32_e32 v3, v3, v14
	v_fma_f32 v8, v34, v3, -v14
	v_cvt_pk_bf16_f32 v9, v8, v8
	ds_write_b16 v7, v9 offset:2080
	v_sub_f32_e32 v3, v3, v15
	v_add_f32_e32 v3, v3, v16
	v_fma_f32 v8, v34, v3, -v16
	v_cvt_pk_bf16_f32 v9, v8, v8
	ds_write_b16 v7, v9 offset:3120
	v_sub_f32_e32 v3, v3, v17
	v_add_f32_e32 v3, v3, v18
	v_fma_f32 v8, v34, v3, -v18
	v_cvt_pk_bf16_f32 v9, v8, v8
	ds_write_b16 v7, v9 offset:4160
	v_sub_f32_e32 v3, v3, v19
	v_add_f32_e32 v3, v3, v20
	v_fma_f32 v8, v34, v3, -v20
	v_cvt_pk_bf16_f32 v9, v8, v8
	ds_write_b16 v7, v9 offset:5200
	v_sub_f32_e32 v3, v3, v21
	v_add_f32_e32 v3, v3, v22
	v_fma_f32 v8, v34, v3, -v22
	v_cvt_pk_bf16_f32 v9, v8, v8
	ds_write_b16 v7, v9 offset:6240
	v_sub_f32_e32 v3, v3, v23
	v_add_f32_e32 v3, v3, v24
	v_fma_f32 v8, v34, v3, -v24
	v_cvt_pk_bf16_f32 v9, v8, v8
	ds_write_b16 v7, v9 offset:7280
	v_sub_f32_e32 v3, v3, v25
	s_cmp_eq_u32 s7, 64
	s_cbranch_scc0 .LBB0_783
	s_branch .Lscan_done
.Lscan_slow:
	s_add_i32 s9, s8, 1
	v_min_i32_e32 v26, s9, v0
	s_add_i32 s9, s8, 2
	v_min_i32_e32 v27, s9, v0
	s_add_i32 s9, s8, 3
	v_min_i32_e32 v28, s9, v0
	s_add_i32 s9, s8, 4
	v_min_i32_e32 v29, s9, v0
	s_add_i32 s9, s8, 5
	v_min_i32_e32 v30, s9, v0
	s_add_i32 s9, s8, 6
	v_min_i32_e32 v31, s9, v0
	s_add_i32 s9, s8, 7
	v_min_i32_e32 v32, s9, v0
	s_add_i32 s9, s8, 8
	v_min_i32_e32 v33, s9, v0
	v_cvt_f32_i32_e32 v26, v26
	v_cvt_f32_i32_e32 v27, v27
	v_cvt_f32_i32_e32 v28, v28
	v_cvt_f32_i32_e32 v29, v29
	v_cvt_f32_i32_e32 v30, v30
	v_cvt_f32_i32_e32 v31, v31
	v_cvt_f32_i32_e32 v32, v32
	v_cvt_f32_i32_e32 v33, v33
	v_rcp_iflag_f32_e32 v26, v26
	v_rcp_iflag_f32_e32 v27, v27
	v_rcp_iflag_f32_e32 v28, v28
	v_rcp_iflag_f32_e32 v29, v29
	v_rcp_iflag_f32_e32 v30, v30
	v_rcp_iflag_f32_e32 v31, v31
	v_rcp_iflag_f32_e32 v32, v32
	v_rcp_iflag_f32_e32 v33, v33
	s_add_i32 s7, s7, 8
	s_addk_i32 s6, 0x2000
	s_addk_i32 s1, 0x2080
	s_waitcnt lgkmcnt(0)
	v_add_f32_e32 v3, v3, v10
	v_fma_f32 v8, v26, v3, -v10
	v_cvt_pk_bf16_f32 v9, v8, v8
	ds_write_b16 v7, v9
	v_sub_f32_e32 v3, v3, v11
	v_add_f32_e32 v3, v3, v12
	v_fma_f32 v8, v27, v3, -v12
	v_cvt_pk_bf16_f32 v9, v8, v8
	ds_write_b16 v7, v9 offset:1040
	v_sub_f32_e32 v3, v3, v13
	v_add_f32_e32 v3, v3, v14
	v_fma_f32 v8, v28, v3, -v14
	v_cvt_pk_bf16_f32 v9, v8, v8
	ds_write_b16 v7, v9 offset:2080
	v_sub_f32_e32 v3, v3, v15
	v_add_f32_e32 v3, v3, v16
	v_fma_f32 v8, v29, v3, -v16
	v_cvt_pk_bf16_f32 v9, v8, v8
	ds_write_b16 v7, v9 offset:3120
	v_sub_f32_e32 v3, v3, v17
	v_add_f32_e32 v3, v3, v18
	v_fma_f32 v8, v30, v3, -v18
	v_cvt_pk_bf16_f32 v9, v8, v8
	ds_write_b16 v7, v9 offset:4160
	v_sub_f32_e32 v3, v3, v19
	v_add_f32_e32 v3, v3, v20
	v_fma_f32 v8, v31, v3, -v20
	v_cvt_pk_bf16_f32 v9, v8, v8
	ds_write_b16 v7, v9 offset:5200
	v_sub_f32_e32 v3, v3, v21
	v_add_f32_e32 v3, v3, v22
	v_fma_f32 v8, v32, v3, -v22
	v_cvt_pk_bf16_f32 v9, v8, v8
	ds_write_b16 v7, v9 offset:6240
	v_sub_f32_e32 v3, v3, v23
	v_add_f32_e32 v3, v3, v24
	v_fma_f32 v8, v33, v3, -v24
	v_cvt_pk_bf16_f32 v9, v8, v8
	ds_write_b16 v7, v9 offset:7280
	v_sub_f32_e32 v3, v3, v25
	s_cmp_eq_u32 s7, 64
	s_cbranch_scc0 .LBB0_783
.Lscan_done:
	s_add_u32 s6, s10, 0xfe01000
	s_addc_u32 s7, s11, 0
	s_ashr_i32 s42, s5, 7
	s_lshr_b32 s8, s5, 5
	s_and_b32 s22, s5, 0xffffff80
	s_add_i32 s0, s42, s2
	s_and_b32 s70, s8, 2
	s_lshl_b32 s8, s22, 1
	s_ashr_i32 s1, s0, 31
	s_add_i32 s8, s8, 0
	s_lshl_b32 s68, s70, 4
	v_bfe_u32 v34, v136, 4, 2
	s_lshl_b64 s[0:1], s[0:1], 15
	s_add_i32 s8, s8, 0x13c00
	s_or_b32 s17, s68, 16
	v_and_b32_e32 v206, 15, v136
	v_lshlrev_b32_e32 v32, 4, v34
	s_add_u32 s0, s10, s0
	v_add_u32_e32 v0, s8, v32
	v_or_b32_e32 v212, s68, v206
	s_movk_i32 s8, 0x410
	s_addc_u32 s1, s11, s1
	v_mov_b32_e32 v33, v197
	v_mad_u32_u24 v1, v212, s8, v0
	v_lshl_add_u64 v[32:33], s[0:1], 0, v[32:33]
	s_mov_b64 s[0:1], 0x3800000
	s_ashr_i32 s39, s38, 31
	s_barrier
	ds_read_b128 v[28:31], v1
	ds_read_b128 v[24:27], v1 offset:64
	ds_read_b128 v[20:23], v1 offset:128
	ds_read_b128 v[16:19], v1 offset:192
	v_or_b32_e32 v1, s17, v206
	v_lshlrev_b32_e32 v207, 3, v34
	v_lshl_add_u64 v[120:121], v[32:33], 0, s[0:1]
	v_lshlrev_b32_e32 v208, 2, v34
	v_lshl_add_u64 v[34:35], s[10:11], 0, v[196:197]
	s_mov_b64 s[0:1], 0x1c801000
	s_or_b32 s12, s38, s68
	s_mov_b32 s13, s39
	v_mad_u32_u24 v0, v1, s8, v0
	v_lshl_add_u64 v[118:119], v[34:35], 0, s[0:1]
	s_lshl_b64 s[0:1], s[12:13], 2
	s_ashr_i32 s8, s22, 4
	s_and_b32 s20, s1, 0x7fffff
	s_and_b32 s21, s0, 0xffffff80
	s_ashr_i32 s9, s8, 31
	s_add_u32 s0, s21, s8
	v_or_b32_e32 v32, s22, v208
	s_addc_u32 s1, s20, s9
	v_ashrrev_i32_e32 v33, 31, v32
	s_lshl_b64 s[0:1], s[0:1], 9
	s_or_b32 s10, s38, s17
	s_mov_b32 s11, s39
	v_lshl_add_u64 v[122:123], v[32:33], 2, s[66:67]
	v_lshl_add_u64 v[32:33], v[118:119], 0, s[0:1]
	s_lshl_b64 s[0:1], s[10:11], 2
	s_and_b32 s24, s1, 0x7fffff
	s_and_b32 s25, s0, 0xffffffc0
	s_add_u32 s0, s25, s8
	v_lshlrev_b32_e32 v34, 8, v206
	v_mov_b32_e32 v35, v197
	s_addc_u32 s1, s24, s9
	v_lshl_add_u64 v[124:125], v[120:121], 0, v[34:35]
	s_lshl_b64 s[0:1], s[0:1], 9
	ds_read_b128 v[12:15], v0
	ds_read_b128 v[8:11], v0 offset:64
	ds_read_b128 v[4:7], v0 offset:128
	ds_read_b128 v[0:3], v0 offset:192
	global_load_dwordx4 v[108:111], v[124:125], off
	global_load_dwordx4 v[104:107], v[124:125], off offset:64
	global_load_dwordx4 v[100:103], v[124:125], off offset:128
	global_load_dwordx4 v[96:99], v[124:125], off offset:192
	global_load_dwordx2 v[112:113], v[32:33], off nt
	v_lshl_add_u64 v[32:33], v[118:119], 0, s[0:1]
	s_or_b32 s0, s22, 16
	s_ashr_i32 s8, s0, 4
	s_ashr_i32 s9, s8, 31
	v_or_b32_e32 v210, 16, v206
	s_add_u32 s0, s21, s8
	global_load_dwordx2 v[132:133], v[32:33], off nt
	v_lshlrev_b32_e32 v32, 8, v210
	v_mov_b32_e32 v33, v197
	s_addc_u32 s1, s20, s9
	v_lshl_add_u64 v[32:33], v[120:121], 0, v[32:33]
	s_lshl_b64 s[0:1], s[0:1], 9
	global_load_dwordx4 v[92:95], v[122:123], off
	global_load_dwordx4 v[88:91], v[32:33], off
	global_load_dwordx4 v[84:87], v[32:33], off offset:64
	global_load_dwordx4 v[80:83], v[32:33], off offset:128
	global_load_dwordx4 v[76:79], v[32:33], off offset:192
	v_lshl_add_u64 v[32:33], v[118:119], 0, s[0:1]
	s_add_u32 s0, s25, s8
	s_addc_u32 s1, s24, s9
	s_lshl_b64 s[0:1], s[0:1], 9
	global_load_dwordx2 v[116:117], v[32:33], off nt
	v_lshl_add_u64 v[32:33], v[118:119], 0, s[0:1]
	s_or_b32 s0, s22, 32
	s_ashr_i32 s8, s0, 4
	s_ashr_i32 s9, s8, 31
	v_or_b32_e32 v211, 32, v206
	s_add_u32 s0, s21, s8
	global_load_dwordx2 v[130:131], v[32:33], off nt
	v_lshlrev_b32_e32 v32, 8, v211
	v_mov_b32_e32 v33, v197
	s_addc_u32 s1, s20, s9
	v_lshl_add_u64 v[32:33], v[120:121], 0, v[32:33]
	s_lshl_b64 s[0:1], s[0:1], 9
	global_load_dwordx4 v[72:75], v[122:123], off offset:64
	global_load_dwordx4 v[68:71], v[32:33], off
	global_load_dwordx4 v[64:67], v[32:33], off offset:64
	global_load_dwordx4 v[60:63], v[32:33], off offset:128
	global_load_dwordx4 v[56:59], v[32:33], off offset:192
	v_lshl_add_u64 v[32:33], v[118:119], 0, s[0:1]
	s_add_u32 s0, s25, s8
	s_addc_u32 s1, s24, s9
	s_lshl_b64 s[0:1], s[0:1], 9
	global_load_dwordx2 v[134:135], v[32:33], off nt
	v_lshl_add_u64 v[32:33], v[118:119], 0, s[0:1]
	s_or_b32 s0, s22, 48
	s_ashr_i32 s8, s0, 4
	s_ashr_i32 s9, s8, 31
	s_add_u32 s0, s21, s8
	v_or_b32_e32 v209, 48, v206
	s_addc_u32 s1, s20, s9
	global_load_dwordx2 v[128:129], v[32:33], off nt
	v_lshlrev_b32_e32 v32, 8, v209
	v_mov_b32_e32 v33, v197
	s_lshl_b64 s[0:1], s[0:1], 9
	v_lshl_add_u64 v[32:33], v[120:121], 0, v[32:33]
	v_lshl_add_u64 v[114:115], v[118:119], 0, s[0:1]
	s_add_u32 s0, s25, s8
	global_load_dwordx4 v[52:55], v[122:123], off offset:128
	global_load_dwordx4 v[48:51], v[32:33], off
	global_load_dwordx4 v[44:47], v[32:33], off offset:64
	global_load_dwordx4 v[40:43], v[32:33], off offset:128
	global_load_dwordx4 v[36:39], v[32:33], off offset:192
	s_addc_u32 s1, s24, s9
	s_lshl_b64 s[0:1], s[0:1], 9
	v_lshl_add_u64 v[126:127], v[118:119], 0, s[0:1]
	global_load_dwordx4 v[32:35], v[122:123], off offset:192
	v_and_b32_e32 v137, 4, v208
	global_load_dwordx2 v[114:115], v[114:115], off nt
	s_nop 0
	global_load_dwordx2 v[126:127], v[126:127], off nt
	s_waitcnt vmcnt(27) lgkmcnt(7)
	v_mfma_f32_16x16x32_bf16 v[138:141], v[108:111], v[28:31], 0
	s_waitcnt vmcnt(23)
	v_lshlrev_b32_e32 v142, 16, v112
	v_lshlrev_b32_e32 v144, 16, v113
	v_and_b32_e32 v146, 0xffff0000, v113
	s_waitcnt lgkmcnt(6)
	v_mfma_f32_16x16x32_bf16 v[138:141], v[104:107], v[24:27], v[138:141]
	v_mul_f32_e32 v113, 0xbfb8aa3b, v142
	v_exp_f32_e32 v113, v113
	v_and_b32_e32 v112, 0xffff0000, v112
	s_waitcnt lgkmcnt(5)
	v_mfma_f32_16x16x32_bf16 v[138:141], v[100:103], v[20:23], v[138:141]
	s_waitcnt vmcnt(21)
	v_mov_b32_e32 v149, v92
	v_add_f32_e32 v113, 1.0, v113
	v_rcp_f32_e32 v148, v113
	s_waitcnt lgkmcnt(4)
	v_mfma_f32_16x16x32_bf16 v[138:141], v[96:99], v[16:19], v[138:141]
	v_mul_f32_e32 v113, 0xbfb8aa3b, v112
	v_exp_f32_e32 v113, v113
	s_lshl_b64 s[0:1], s[12:13], 1
	s_ashr_i32 s26, s22, 5
	s_and_b32 s13, s1, 0x3fffff
	s_nop 2
	v_mov_b32_e32 v143, v138
	v_pk_mul_f32 v[142:143], v[148:149], v[142:143]
	v_add_f32_e32 v113, 1.0, v113
	v_mul_f32_e32 v138, v142, v143
	v_rcp_f32_e32 v142, v113
	v_mov_b32_e32 v143, v93
	v_mov_b32_e32 v113, v139
	v_mov_b32_e32 v145, v140
	v_pk_mul_f32 v[112:113], v[142:143], v[112:113]
	s_and_b32 s19, s0, 0xffffffc0
	v_mul_f32_e32 v112, v112, v113
	v_cvt_pk_bf16_f32 v138, v138, v112
	v_mul_f32_e32 v112, 0xbfb8aa3b, v144
	v_exp_f32_e32 v112, v112
	v_mov_b32_e32 v113, v94
	v_mov_b32_e32 v147, v141
	s_ashr_i32 s27, s26, 31
	v_add_f32_e32 v112, 1.0, v112
	v_rcp_f32_e32 v112, v112
	s_add_u32 s0, s19, s26
	s_addc_u32 s1, s13, s27
	s_lshl_b64 s[0:1], s[0:1], 10
	v_pk_mul_f32 v[112:113], v[112:113], v[144:145]
	s_add_u32 s0, s6, s0
	v_mul_f32_e32 v139, v112, v113
	v_mul_f32_e32 v112, 0xbfb8aa3b, v146
	v_exp_f32_e32 v112, v112
	v_mov_b32_e32 v113, v95
	s_addc_u32 s1, s7, s1
	v_lshlrev_b32_e32 v184, 1, v137
	v_add_f32_e32 v112, 1.0, v112
	v_rcp_f32_e32 v112, v112
	v_mov_b32_e32 v185, v197
	s_waitcnt vmcnt(16)
	v_lshlrev_b32_e32 v142, 16, v116
	v_lshlrev_b32_e32 v144, 16, v117
	v_pk_mul_f32 v[112:113], v[112:113], v[146:147]
	v_and_b32_e32 v146, 0xffff0000, v117
	v_mul_f32_e32 v112, v112, v113
	v_cvt_pk_bf16_f32 v139, v139, v112
	v_lshrrev_b32_e32 v112, 1, v136
	v_and_or_b32 v112, v112, 16, v206
	v_lshlrev_b32_e32 v112, 4, v112
	v_mov_b32_e32 v113, v197
	v_lshl_add_u64 v[140:141], s[0:1], 0, v[112:113]
	v_lshl_add_u64 v[140:141], v[140:141], 0, v[184:185]
	global_store_dwordx2 v[140:141], v[138:139], off
	v_mfma_f32_16x16x32_bf16 v[138:141], v[88:91], v[28:31], 0
	v_mul_f32_e32 v117, 0xbfb8aa3b, v142
	v_exp_f32_e32 v117, v117
	v_and_b32_e32 v116, 0xffff0000, v116
	v_mfma_f32_16x16x32_bf16 v[138:141], v[84:87], v[24:27], v[138:141]
	s_waitcnt vmcnt(15)
	v_mov_b32_e32 v149, v72
	v_add_f32_e32 v117, 1.0, v117
	v_rcp_f32_e32 v148, v117
	v_mfma_f32_16x16x32_bf16 v[138:141], v[80:83], v[20:23], v[138:141]
	v_mul_f32_e32 v117, 0xbfb8aa3b, v116
	v_exp_f32_e32 v117, v117
	v_or_b32_e32 v213, 16, v208
	v_mfma_f32_16x16x32_bf16 v[138:141], v[76:79], v[16:19], v[138:141]
	s_or_b32 s33, s26, 1
	v_add_f32_e32 v117, 1.0, v117
	s_ashr_i32 s34, s33, 31
	s_waitcnt lgkmcnt(3)
	v_mfma_f32_16x16x32_bf16 v[108:111], v[108:111], v[12:15], 0
	v_or_b32_e32 v222, 48, v208
	s_nop 1
	v_mov_b32_e32 v143, v138
	v_pk_mul_f32 v[142:143], v[148:149], v[142:143]
	v_mov_b32_e32 v145, v140
	v_mul_f32_e32 v137, v142, v143
	v_rcp_f32_e32 v142, v117
	v_mov_b32_e32 v143, v73
	v_mov_b32_e32 v117, v139
	v_mov_b32_e32 v147, v141
	v_pk_mul_f32 v[116:117], v[142:143], v[116:117]
	s_waitcnt vmcnt(10)
	v_lshlrev_b32_e32 v142, 16, v134
	v_mul_f32_e32 v116, v116, v117
	v_cvt_pk_bf16_f32 v138, v137, v116
	v_mul_f32_e32 v116, 0xbfb8aa3b, v144
	v_exp_f32_e32 v116, v116
	v_mov_b32_e32 v117, v74
	v_and_b32_e32 v134, 0xffff0000, v134
	s_waitcnt vmcnt(8)
	v_mov_b32_e32 v149, v52
	v_add_f32_e32 v116, 1.0, v116
	v_rcp_f32_e32 v116, v116
	s_waitcnt lgkmcnt(2)
	v_mfma_f32_16x16x32_bf16 v[104:107], v[104:107], v[8:11], v[108:111]
	v_or_b32_e32 v238, 0x60, v206
	v_or_b32_e32 v223, 0x70, v206
	v_pk_mul_f32 v[116:117], v[116:117], v[144:145]
	v_lshlrev_b32_e32 v144, 16, v135
	v_mul_f32_e32 v137, v116, v117
	v_mul_f32_e32 v116, 0xbfb8aa3b, v146
	v_exp_f32_e32 v116, v116
	v_mov_b32_e32 v117, v75
	s_waitcnt lgkmcnt(1)
	v_mfma_f32_16x16x32_bf16 v[100:103], v[100:103], v[4:7], v[104:107]
	v_mov_b32_e32 v109, v92
	v_add_f32_e32 v116, 1.0, v116
	v_rcp_f32_e32 v116, v116
	v_mfma_f32_16x16x32_bf16 v[88:91], v[88:91], v[12:15], 0
	v_lshlrev_b32_e32 v104, 16, v133
	v_and_b32_e32 v106, 0xffff0000, v133
	v_pk_mul_f32 v[116:117], v[116:117], v[146:147]
	v_and_b32_e32 v146, 0xffff0000, v135
	v_mul_f32_e32 v116, v116, v117
	v_cvt_pk_bf16_f32 v139, v137, v116
	v_lshlrev_b32_e32 v116, 1, v213
	v_and_or_b32 v116, v116, 48, v206
	v_lshlrev_b32_e32 v116, 4, v116
	v_mov_b32_e32 v117, v197
	v_lshl_add_u64 v[140:141], s[0:1], 0, v[116:117]
	v_lshl_add_u64 v[140:141], v[140:141], 0, v[184:185]
	global_store_dwordx2 v[140:141], v[138:139], off
	v_mfma_f32_16x16x32_bf16 v[138:141], v[68:71], v[28:31], 0
	v_mul_f32_e32 v135, 0xbfb8aa3b, v142
	v_exp_f32_e32 v135, v135
	s_add_u32 s0, s19, s33
	v_mfma_f32_16x16x32_bf16 v[138:141], v[64:67], v[24:27], v[138:141]
	s_addc_u32 s1, s13, s34
	v_add_f32_e32 v135, 1.0, v135
	v_rcp_f32_e32 v148, v135
	v_mfma_f32_16x16x32_bf16 v[138:141], v[60:63], v[20:23], v[138:141]
	v_mul_f32_e32 v135, 0xbfb8aa3b, v134
	v_exp_f32_e32 v135, v135
	s_lshl_b64 s[0:1], s[0:1], 10
	v_mfma_f32_16x16x32_bf16 v[138:141], v[56:59], v[16:19], v[138:141]
	s_add_u32 s0, s6, s0
	v_add_f32_e32 v135, 1.0, v135
	s_addc_u32 s1, s7, s1
	s_waitcnt lgkmcnt(0)
	v_mfma_f32_16x16x32_bf16 v[96:99], v[96:99], v[0:3], v[100:103]
	s_nop 2
	v_and_b32_e32 v102, 0xffff0000, v132
	v_mov_b32_e32 v143, v138
	v_pk_mul_f32 v[142:143], v[148:149], v[142:143]
	v_mov_b32_e32 v145, v140
	v_mul_f32_e32 v137, v142, v143
	v_rcp_f32_e32 v142, v135
	v_mov_b32_e32 v143, v53
	v_mov_b32_e32 v135, v139
	v_mov_b32_e32 v139, v54
	v_pk_mul_f32 v[134:135], v[142:143], v[134:135]
	v_mov_b32_e32 v147, v141
	v_mul_f32_e32 v134, v134, v135
	v_mul_f32_e32 v135, 0xbfb8aa3b, v144
	v_exp_f32_e32 v135, v135
	v_cvt_pk_bf16_f32 v134, v137, v134
	v_mul_f32_e32 v137, 0xbfb8aa3b, v146
	v_exp_f32_e32 v137, v137
	v_add_f32_e32 v135, 1.0, v135
	v_rcp_f32_e32 v138, v135
	s_waitcnt vmcnt(3)
	v_lshlrev_b32_e32 v142, 16, v115
	v_add_f32_e32 v137, 1.0, v137
	v_mfma_f32_16x16x32_bf16 v[84:87], v[84:87], v[8:11], v[88:91]
	v_mul_f32_e64 v138, v138, v144
	v_mul_f32_e64 v139, v139, v145
	v_and_b32_e32 v144, 0xffff0000, v115
	v_mul_f32_e32 v135, v138, v139
	v_rcp_f32_e32 v138, v137
	v_mov_b32_e32 v139, v55
	v_mul_f32_e32 v92, 0xbfb8aa3b, v102
	v_exp_f32_e32 v92, v92
	v_pk_mul_f32 v[138:139], v[138:139], v[146:147]
	v_mov_b32_e32 v147, v32
	v_mul_f32_e32 v137, v138, v139
	v_lshl_add_u64 v[138:139], s[0:1], 0, v[112:113]
	v_lshl_add_u64 v[138:139], v[138:139], 0, v[184:185]
	v_cvt_pk_bf16_f32 v135, v135, v137
	global_store_dwordx2 v[138:139], v[134:135], off
	v_mfma_f32_16x16x32_bf16 v[138:141], v[48:51], v[28:31], 0
	v_lshlrev_b32_e32 v134, 16, v114
	v_mul_f32_e32 v115, 0xbfb8aa3b, v134
	v_exp_f32_e32 v115, v115
	v_mfma_f32_16x16x32_bf16 v[138:141], v[44:47], v[24:27], v[138:141]
	v_and_b32_e32 v114, 0xffff0000, v114
	v_lshlrev_b32_e32 v100, 16, v132
	v_add_f32_e32 v115, 1.0, v115
	v_mfma_f32_16x16x32_bf16 v[138:141], v[40:43], v[20:23], v[138:141]
	v_rcp_f32_e32 v146, v115
	v_mul_f32_e32 v115, 0xbfb8aa3b, v114
	v_exp_f32_e32 v115, v115
	v_mfma_f32_16x16x32_bf16 v[138:141], v[36:39], v[16:19], v[138:141]
	v_mul_f32_e32 v101, 0xbfb8aa3b, v100
	v_add_f32_e32 v92, 1.0, v92
	v_add_f32_e32 v115, 1.0, v115
	v_mfma_f32_16x16x32_bf16 v[80:83], v[80:83], v[4:7], v[84:87]
	v_exp_f32_e32 v101, v101
	s_nop 2
	v_mov_b32_e32 v135, v138
	v_pk_mul_f32 v[134:135], v[146:147], v[134:135]
	v_mov_b32_e32 v143, v140
	v_mul_f32_e32 v137, v134, v135
	v_rcp_f32_e32 v134, v115
	v_mov_b32_e32 v135, v33
	v_mov_b32_e32 v115, v139
	v_mfma_f32_16x16x32_bf16 v[68:71], v[68:71], v[12:15], 0
	v_mul_f32_e64 v114, v134, v114
	v_mul_f32_e64 v115, v135, v115
	v_rcp_f32_e32 v92, v92
	v_mul_f32_e32 v114, v114, v115
	v_cvt_pk_bf16_f32 v134, v137, v114
	v_mul_f32_e32 v114, 0xbfb8aa3b, v142
	v_exp_f32_e32 v114, v114
	v_mov_b32_e32 v115, v34
	v_mfma_f32_16x16x32_bf16 v[76:79], v[76:79], v[0:3], v[80:83]
	v_mov_b32_e32 v89, v72
	v_add_f32_e32 v114, 1.0, v114
	v_rcp_f32_e32 v114, v114
	v_and_b32_e32 v82, 0xffff0000, v130
	v_mfma_f32_16x16x32_bf16 v[64:67], v[64:67], v[8:11], v[68:71]
	v_mul_f32_e32 v72, 0xbfb8aa3b, v82
	v_pk_mul_f32 v[114:115], v[114:115], v[142:143]
	v_mov_b32_e32 v145, v141
	v_mul_f32_e32 v135, v114, v115
	v_mul_f32_e32 v114, 0xbfb8aa3b, v144
	v_exp_f32_e32 v114, v114
	v_mov_b32_e32 v115, v35
	v_mov_b32_e32 v103, v97
	v_exp_f32_e32 v72, v72
	v_add_f32_e32 v114, 1.0, v114
	v_rcp_f32_e32 v114, v114
	v_add_f32_e32 v101, 1.0, v101
	v_pk_mul_f32 v[92:93], v[92:93], v[102:103]
	v_rcp_f32_e32 v108, v101
	v_pk_mul_f32 v[114:115], v[114:115], v[144:145]
	v_mul_f32_e32 v92, v92, v93
	v_mul_f32_e32 v114, v114, v115
	v_mul_f32_e32 v93, 0xbfb8aa3b, v104
	v_mov_b32_e32 v97, v94
	v_mul_f32_e32 v94, 0xbfb8aa3b, v106
	v_mfma_f32_16x16x32_bf16 v[60:63], v[60:63], v[4:7], v[64:67]
	v_cvt_pk_bf16_f32 v135, v135, v114
	v_lshlrev_b32_e32 v114, 1, v222
	v_exp_f32_e32 v93, v93
	v_mfma_f32_16x16x32_bf16 v[48:51], v[48:51], v[12:15], 0
	v_exp_f32_e32 v94, v94
	v_lshlrev_b32_e32 v80, 16, v130
	v_and_or_b32 v114, v114, 48, v206
	v_mul_f32_e32 v81, 0xbfb8aa3b, v80
	v_add_f32_e32 v72, 1.0, v72
	v_lshlrev_b32_e32 v114, 4, v114
	v_mov_b32_e32 v115, v197
	v_mov_b32_e32 v101, v96
	v_exp_f32_e32 v81, v81
	v_rcp_f32_e32 v72, v72
	v_lshl_add_u64 v[138:139], s[0:1], 0, v[114:115]
	v_pk_mul_f32 v[100:101], v[108:109], v[100:101]
	v_mfma_f32_16x16x32_bf16 v[56:59], v[56:59], v[0:3], v[60:63]
	v_lshl_add_u64 v[138:139], v[138:139], 0, v[184:185]
	s_lshl_b64 s[0:1], s[10:11], 1
	v_mul_f32_e32 v96, v100, v101
	v_and_b32_e32 v62, 0xffff0000, v128
	v_mfma_f32_16x16x32_bf16 v[44:47], v[44:47], v[8:11], v[48:51]
	v_add_f32_e32 v93, 1.0, v93
	v_add_f32_e32 v94, 1.0, v94
	v_mov_b32_e32 v69, v52
	v_mul_f32_e32 v52, 0xbfb8aa3b, v62
	global_store_dwordx2 v[138:139], v[134:135], off
	s_and_b32 s8, s1, 0x3fffff
	s_and_b32 s9, s0, 0xffffffe0
	v_cvt_pk_bf16_f32 v92, v96, v92
	v_rcp_f32_e32 v96, v93
	v_rcp_f32_e32 v94, v94
	v_mov_b32_e32 v83, v77
	v_exp_f32_e32 v52, v52
	s_add_u32 s0, s9, s26
	v_lshlrev_b32_e32 v84, 16, v131
	v_and_b32_e32 v86, 0xffff0000, v131
	v_add_f32_e32 v81, 1.0, v81
	v_pk_mul_f32 v[72:73], v[72:73], v[82:83]
	s_addc_u32 s1, s8, s27
	v_rcp_f32_e32 v88, v81
	v_mul_f32_e32 v72, v72, v73
	v_mul_f32_e32 v73, 0xbfb8aa3b, v84
	v_mov_b32_e32 v77, v74
	v_mul_f32_e32 v74, 0xbfb8aa3b, v86
	v_mfma_f32_16x16x32_bf16 v[40:43], v[40:43], v[4:7], v[44:47]
	v_mov_b32_e32 v105, v98
	v_mov_b32_e32 v107, v99
	s_lshl_b64 s[0:1], s[0:1], 10
	v_exp_f32_e32 v73, v73
	v_exp_f32_e32 v74, v74
	v_lshlrev_b32_e32 v60, 16, v128
	v_pk_mul_f32 v[96:97], v[96:97], v[104:105]
	v_pk_mul_f32 v[94:95], v[94:95], v[106:107]
	s_add_u32 s0, s6, s0
	v_mul_f32_e32 v61, 0xbfb8aa3b, v60
	v_add_f32_e32 v52, 1.0, v52
	v_mul_f32_e32 v93, v96, v97
	v_mul_f32_e32 v94, v94, v95
	s_addc_u32 s1, s7, s1
	v_mov_b32_e32 v81, v76
	v_exp_f32_e32 v61, v61
	v_rcp_f32_e32 v52, v52
	v_cvt_pk_bf16_f32 v93, v93, v94
	v_lshl_add_u64 v[94:95], s[0:1], 0, v[112:113]
	v_pk_mul_f32 v[80:81], v[88:89], v[80:81]
	v_mfma_f32_16x16x32_bf16 v[36:39], v[36:39], v[0:3], v[40:43]
	v_lshl_add_u64 v[94:95], v[94:95], 0, v[184:185]
	v_mul_f32_e32 v76, v80, v81
	v_add_f32_e32 v73, 1.0, v73
	s_waitcnt vmcnt(4)
	v_and_b32_e32 v42, 0xffff0000, v126
	v_add_f32_e32 v74, 1.0, v74
	v_mov_b32_e32 v49, v32
	v_mul_f32_e32 v32, 0xbfb8aa3b, v42
	global_store_dwordx2 v[94:95], v[92:93], off
	v_cvt_pk_bf16_f32 v72, v76, v72
	v_rcp_f32_e32 v76, v73
	v_rcp_f32_e32 v74, v74
	v_mov_b32_e32 v63, v57
	v_exp_f32_e32 v32, v32
	v_lshlrev_b32_e32 v64, 16, v129
	v_and_b32_e32 v66, 0xffff0000, v129
	v_add_f32_e32 v61, 1.0, v61
	v_pk_mul_f32 v[52:53], v[52:53], v[62:63]
	v_rcp_f32_e32 v68, v61
	v_mul_f32_e32 v52, v52, v53
	v_mul_f32_e32 v53, 0xbfb8aa3b, v64
	v_mov_b32_e32 v57, v54
	v_mul_f32_e32 v54, 0xbfb8aa3b, v66
	v_mov_b32_e32 v85, v78
	v_mov_b32_e32 v87, v79
	v_exp_f32_e32 v53, v53
	v_exp_f32_e32 v54, v54
	v_lshlrev_b32_e32 v40, 16, v126
	v_pk_mul_f32 v[76:77], v[76:77], v[84:85]
	v_pk_mul_f32 v[74:75], v[74:75], v[86:87]
	v_mul_f32_e32 v41, 0xbfb8aa3b, v40
	v_add_f32_e32 v32, 1.0, v32
	v_mul_f32_e32 v73, v76, v77
	v_mul_f32_e32 v74, v74, v75
	v_mov_b32_e32 v61, v56
	v_exp_f32_e32 v41, v41
	v_rcp_f32_e32 v32, v32
	v_cvt_pk_bf16_f32 v73, v73, v74
	v_lshl_add_u64 v[74:75], s[0:1], 0, v[116:117]
	v_pk_mul_f32 v[60:61], v[68:69], v[60:61]
	v_lshl_add_u64 v[74:75], v[74:75], 0, v[184:185]
	v_mul_f32_e32 v56, v60, v61
	v_add_f32_e32 v53, 1.0, v53
	v_add_f32_e32 v54, 1.0, v54
	global_store_dwordx2 v[74:75], v[72:73], off
	v_cvt_pk_bf16_f32 v52, v56, v52
	v_rcp_f32_e32 v56, v53
	v_rcp_f32_e32 v54, v54
	v_mov_b32_e32 v43, v37
	s_add_u32 s0, s9, s33
	v_lshlrev_b32_e32 v44, 16, v127
	v_and_b32_e32 v46, 0xffff0000, v127
	v_add_f32_e32 v41, 1.0, v41
	v_pk_mul_f32 v[32:33], v[32:33], v[42:43]
	s_addc_u32 s1, s8, s34
	v_rcp_f32_e32 v48, v41
	v_mul_f32_e32 v32, v32, v33
	v_mul_f32_e32 v33, 0xbfb8aa3b, v44
	v_mov_b32_e32 v37, v34
	v_mul_f32_e32 v34, 0xbfb8aa3b, v46
	v_mov_b32_e32 v65, v58
	v_mov_b32_e32 v67, v59
	s_lshl_b64 s[0:1], s[0:1], 10
	v_exp_f32_e32 v33, v33
	v_exp_f32_e32 v34, v34
	v_pk_mul_f32 v[56:57], v[56:57], v[64:65]
	v_pk_mul_f32 v[54:55], v[54:55], v[66:67]
	s_add_u32 s0, s6, s0
	v_mul_f32_e32 v53, v56, v57
	v_mul_f32_e32 v54, v54, v55
	s_addc_u32 s1, s7, s1
	v_mov_b32_e32 v41, v36
	v_cvt_pk_bf16_f32 v53, v53, v54
	v_lshl_add_u64 v[54:55], s[0:1], 0, v[112:113]
	v_pk_mul_f32 v[40:41], v[48:49], v[40:41]
	v_lshl_add_u64 v[54:55], v[54:55], 0, v[184:185]
	v_mul_f32_e32 v36, v40, v41
	v_add_f32_e32 v33, 1.0, v33
	v_add_f32_e32 v34, 1.0, v34
	global_store_dwordx2 v[54:55], v[52:53], off
	v_cvt_pk_bf16_f32 v32, v36, v32
	v_rcp_f32_e32 v36, v33
	v_rcp_f32_e32 v34, v34
	v_mov_b32_e32 v45, v38
	v_mov_b32_e32 v47, v39
	v_pk_mul_f32 v[36:37], v[36:37], v[44:45]
	v_pk_mul_f32 v[34:35], v[34:35], v[46:47]
	v_mul_f32_e32 v33, v36, v37
	v_mul_f32_e32 v34, v34, v35
	v_cvt_pk_bf16_f32 v33, v33, v34
	v_lshl_add_u64 v[34:35], s[0:1], 0, v[114:115]
	v_lshl_add_u64 v[34:35], v[34:35], 0, v[184:185]
	global_store_dwordx2 v[34:35], v[32:33], off
	v_add_co_u32_e32 v32, vcc, s71, v124
	s_movk_i32 s0, 0x5000
	s_nop 0
	v_addc_co_u32_e32 v33, vcc, 0, v125, vcc
	v_add_co_u32_e32 v34, vcc, s0, v124
	s_or_b32 s0, s22, 64
	s_ashr_i32 s10, s0, 4
	s_ashr_i32 s11, s10, 31
	s_add_u32 s0, s21, s10
	s_addc_u32 s1, s20, s11
	v_addc_co_u32_e32 v35, vcc, 0, v125, vcc
	s_lshl_b64 s[0:1], s[0:1], 9
	global_load_dwordx4 v[108:111], v[34:35], off offset:-4096
	global_load_dwordx4 v[104:107], v[32:33], off offset:64
	global_load_dwordx4 v[100:103], v[32:33], off offset:128
	global_load_dwordx4 v[96:99], v[32:33], off offset:192
	v_lshl_add_u64 v[32:33], v[118:119], 0, s[0:1]
	s_add_u32 s0, s25, s10
	s_addc_u32 s1, s24, s11
	s_lshl_b64 s[0:1], s[0:1], 9
	global_load_dwordx2 v[134:135], v[32:33], off nt
	v_lshl_add_u64 v[32:33], v[118:119], 0, s[0:1]
	s_or_b32 s0, s22, 0x50
	s_ashr_i32 s10, s0, 4
	s_ashr_i32 s11, s10, 31
	s_add_u32 s0, s21, s10
	s_addc_u32 s1, s20, s11
	s_lshl_b64 s[0:1], s[0:1], 9
	global_load_dwordx4 v[92:95], v[122:123], off offset:256
	global_load_dwordx2 v[128:129], v[32:33], off nt
	global_load_dwordx4 v[88:91], v[34:35], off
	global_load_dwordx4 v[84:87], v[34:35], off offset:64
	global_load_dwordx4 v[80:83], v[34:35], off offset:128
	global_load_dwordx4 v[76:79], v[34:35], off offset:192
	v_lshl_add_u64 v[32:33], v[118:119], 0, s[0:1]
	s_add_u32 s0, s25, s10
	s_addc_u32 s1, s24, s11
	s_lshl_b64 s[0:1], s[0:1], 9
	global_load_dwordx2 v[132:133], v[32:33], off nt
	v_lshl_add_u64 v[32:33], v[118:119], 0, s[0:1]
	s_or_b32 s0, s22, 0x60
	s_ashr_i32 s10, s0, 4
	s_ashr_i32 s11, s10, 31
	s_add_u32 s0, s21, s10
	global_load_dwordx2 v[126:127], v[32:33], off nt
	v_lshlrev_b32_e32 v32, 8, v238
	v_mov_b32_e32 v33, v197
	s_addc_u32 s1, s20, s11
	v_lshl_add_u64 v[32:33], v[120:121], 0, v[32:33]
	s_lshl_b64 s[0:1], s[0:1], 9
	global_load_dwordx4 v[72:75], v[122:123], off offset:320
	global_load_dwordx4 v[68:71], v[32:33], off
	global_load_dwordx4 v[64:67], v[32:33], off offset:64
	global_load_dwordx4 v[60:63], v[32:33], off offset:128
	global_load_dwordx4 v[56:59], v[32:33], off offset:192
	v_lshl_add_u64 v[32:33], v[118:119], 0, s[0:1]
	s_add_u32 s0, s25, s10
	s_addc_u32 s1, s24, s11
	s_lshl_b64 s[0:1], s[0:1], 9
	global_load_dwordx2 v[130:131], v[32:33], off nt
	v_lshl_add_u64 v[32:33], v[118:119], 0, s[0:1]
	s_or_b32 s0, s22, 0x70
	s_ashr_i32 s10, s0, 4
	s_ashr_i32 s11, s10, 31
	s_add_u32 s0, s21, s10
	s_addc_u32 s1, s20, s11
	global_load_dwordx2 v[124:125], v[32:33], off nt
	v_lshlrev_b32_e32 v32, 8, v223
	v_mov_b32_e32 v33, v197
	s_lshl_b64 s[0:1], s[0:1], 9
	v_lshl_add_u64 v[32:33], v[120:121], 0, v[32:33]
	v_lshl_add_u64 v[120:121], v[118:119], 0, s[0:1]
	s_add_u32 s0, s25, s10
	global_load_dwordx4 v[52:55], v[122:123], off offset:384
	global_load_dwordx4 v[48:51], v[32:33], off
	global_load_dwordx4 v[44:47], v[32:33], off offset:64
	global_load_dwordx4 v[40:43], v[32:33], off offset:128
	global_load_dwordx4 v[36:39], v[32:33], off offset:192
	s_addc_u32 s1, s24, s11
	s_lshl_b64 s[0:1], s[0:1], 9
	v_lshl_add_u64 v[118:119], v[118:119], 0, s[0:1]
	global_load_dwordx4 v[32:35], v[122:123], off offset:448
	s_nop 0
	global_load_dwordx2 v[120:121], v[120:121], off nt
	s_nop 0
	global_load_dwordx2 v[118:119], v[118:119], off nt
	s_waitcnt vmcnt(27)
	v_mfma_f32_16x16x32_bf16 v[138:141], v[108:111], v[28:31], 0
	s_waitcnt vmcnt(23)
	v_lshlrev_b32_e32 v122, 16, v134
	v_mul_f32_e32 v123, 0xbfb8aa3b, v122
	v_exp_f32_e32 v123, v123
	v_mfma_f32_16x16x32_bf16 v[138:141], v[104:107], v[24:27], v[138:141]
	s_waitcnt vmcnt(22)
	v_mov_b32_e32 v147, v92
	v_and_b32_e32 v134, 0xffff0000, v134
	v_add_f32_e32 v123, 1.0, v123
	v_mfma_f32_16x16x32_bf16 v[138:141], v[100:103], v[20:23], v[138:141]
	v_rcp_f32_e32 v146, v123
	v_lshlrev_b32_e32 v142, 16, v135
	v_and_b32_e32 v144, 0xffff0000, v135
	v_mfma_f32_16x16x32_bf16 v[138:141], v[96:99], v[16:19], v[138:141]
	s_or_b32 s11, s26, 2
	s_ashr_i32 s20, s11, 31
	s_add_u32 s0, s19, s11
	s_addc_u32 s1, s13, s20
	s_lshl_b64 s[0:1], s[0:1], 10
	s_nop 2
	v_mov_b32_e32 v123, v138
	v_pk_mul_f32 v[122:123], v[146:147], v[122:123]
	v_mov_b32_e32 v135, v139
	v_mul_f32_e32 v137, v122, v123
	v_mul_f32_e32 v122, 0xbfb8aa3b, v134
	v_exp_f32_e32 v122, v122
	v_mov_b32_e32 v123, v93
	v_mov_b32_e32 v143, v140
	v_mov_b32_e32 v145, v141
	v_add_f32_e32 v122, 1.0, v122
	v_rcp_f32_e32 v122, v122
	s_waitcnt vmcnt(20)
	v_mfma_f32_16x16x32_bf16 v[138:141], v[88:91], v[28:31], 0
	s_add_u32 s0, s6, s0
	s_addc_u32 s1, s7, s1
	v_pk_mul_f32 v[122:123], v[122:123], v[134:135]
	v_mov_b32_e32 v135, v94
	v_mul_f32_e32 v122, v122, v123
	v_mul_f32_e32 v123, 0xbfb8aa3b, v142
	v_exp_f32_e32 v123, v123
	v_cvt_pk_bf16_f32 v122, v137, v122
	s_waitcnt vmcnt(19)
	v_mfma_f32_16x16x32_bf16 v[138:141], v[84:87], v[24:27], v[138:141]
	v_and_b32_e32 v220, 63, v136
	v_add_f32_e32 v123, 1.0, v123
	v_rcp_f32_e32 v134, v123
	s_waitcnt vmcnt(18)
	v_mfma_f32_16x16x32_bf16 v[138:141], v[80:83], v[20:23], v[138:141]
	v_lshlrev_b32_e32 v186, 4, v220
	v_lshlrev_b32_e32 v188, 1, v207
	v_pk_mul_f32 v[134:135], v[134:135], v[142:143]
	s_waitcnt vmcnt(17)
	v_mfma_f32_16x16x32_bf16 v[138:141], v[76:79], v[16:19], v[138:141]
	v_mul_f32_e32 v123, v134, v135
	v_mul_f32_e32 v134, 0xbfb8aa3b, v144
	v_exp_f32_e32 v134, v134
	v_mov_b32_e32 v135, v95
	s_waitcnt vmcnt(16)
	v_and_b32_e32 v142, 0xffff0000, v133
	s_nop 1
	v_mov_b32_e32 v143, v141
	v_add_f32_e32 v134, 1.0, v134
	v_rcp_f32_e32 v134, v134
	v_not_b32_e32 v219, v208
	v_or_b32_e32 v218, 2, v208
	v_or_b32_e32 v217, 3, v208
	v_pk_mul_f32 v[134:135], v[134:135], v[144:145]
	s_waitcnt vmcnt(14)
	v_mov_b32_e32 v145, v72
	v_mul_f32_e32 v134, v134, v135
	v_cvt_pk_bf16_f32 v123, v123, v134
	v_lshl_add_u64 v[134:135], s[0:1], 0, v[112:113]
	v_lshl_add_u64 v[134:135], v[134:135], 0, v[184:185]
	global_store_dwordx2 v[134:135], v[122:123], off
	v_lshlrev_b32_e32 v122, 16, v132
	v_mul_f32_e32 v123, 0xbfb8aa3b, v122
	v_exp_f32_e32 v123, v123
	v_and_b32_e32 v132, 0xffff0000, v132
	v_lshlrev_b32_e32 v134, 16, v133
	v_mov_b32_e32 v133, v139
	v_add_f32_e32 v123, 1.0, v123
	v_rcp_f32_e32 v144, v123
	v_mov_b32_e32 v123, v138
	s_waitcnt vmcnt(10)
	v_lshlrev_b32_e32 v138, 16, v131
	v_or_b32_e32 v216, 17, v208
	v_pk_mul_f32 v[122:123], v[144:145], v[122:123]
	v_or_b32_e32 v215, 18, v208
	v_mul_f32_e32 v135, v122, v123
	v_mul_f32_e32 v122, 0xbfb8aa3b, v132
	v_exp_f32_e32 v122, v122
	v_mov_b32_e32 v123, v73
	v_or_b32_e32 v214, 19, v208
	v_readlane_b32 s27, v255, 46
	v_add_f32_e32 v122, 1.0, v122
	v_rcp_f32_e32 v122, v122
	s_nop 0
	v_pk_mul_f32 v[122:123], v[122:123], v[132:133]
	s_nop 0
	v_mul_f32_e32 v122, v122, v123
	v_mul_f32_e32 v123, 0xbfb8aa3b, v134
	v_exp_f32_e32 v123, v123
	v_cvt_pk_bf16_f32 v122, v135, v122
	v_mov_b32_e32 v133, v74
	v_mov_b32_e32 v135, v140
	v_add_f32_e32 v123, 1.0, v123
	v_rcp_f32_e32 v132, v123
	v_and_b32_e32 v140, 0xffff0000, v131
	v_pk_mul_f32 v[132:133], v[132:133], v[134:135]
	s_nop 0
	v_mul_f32_e32 v123, v132, v133
	v_mul_f32_e32 v132, 0xbfb8aa3b, v142
	v_exp_f32_e32 v132, v132
	v_mov_b32_e32 v133, v75
	v_add_f32_e32 v132, 1.0, v132
	v_rcp_f32_e32 v132, v132
	s_nop 0
	v_pk_mul_f32 v[132:133], v[132:133], v[142:143]
	s_nop 0
	v_mul_f32_e32 v132, v132, v133
	v_cvt_pk_bf16_f32 v123, v123, v132
	v_lshl_add_u64 v[132:133], s[0:1], 0, v[116:117]
	v_lshl_add_u64 v[132:133], v[132:133], 0, v[184:185]
	global_store_dwordx2 v[132:133], v[122:123], off
	v_mfma_f32_16x16x32_bf16 v[132:135], v[68:71], v[28:31], 0
	v_lshlrev_b32_e32 v122, 16, v130
	v_mul_f32_e32 v123, 0xbfb8aa3b, v122
	v_exp_f32_e32 v123, v123
	v_mfma_f32_16x16x32_bf16 v[132:135], v[64:67], v[24:27], v[132:135]
	s_waitcnt vmcnt(9)
	v_mov_b32_e32 v143, v52
	v_and_b32_e32 v130, 0xffff0000, v130
	v_add_f32_e32 v123, 1.0, v123
	v_mfma_f32_16x16x32_bf16 v[132:135], v[60:63], v[20:23], v[132:135]
	v_rcp_f32_e32 v142, v123
	s_ashr_i32 s0, s5, 5
	s_or_b32 s5, s0, 3
	v_mfma_f32_16x16x32_bf16 v[132:135], v[56:59], v[16:19], v[132:135]
	s_ashr_i32 s10, s5, 31
	s_add_u32 s0, s19, s5
	s_addc_u32 s1, s13, s10
	s_waitcnt vmcnt(8)
	v_mfma_f32_16x16x32_bf16 v[28:31], v[48:51], v[28:31], 0
	s_lshl_b64 s[0:1], s[0:1], 10
	s_nop 1
	v_mov_b32_e32 v123, v132
	v_pk_mul_f32 v[122:123], v[142:143], v[122:123]
	s_waitcnt vmcnt(7)
	v_mfma_f32_16x16x32_bf16 v[24:27], v[44:47], v[24:27], v[28:31]
	v_mul_f32_e32 v132, v122, v123
	v_mul_f32_e32 v122, 0xbfb8aa3b, v130
	v_exp_f32_e32 v122, v122
	v_mov_b32_e32 v123, v53
	v_mov_b32_e32 v131, v133
	s_waitcnt vmcnt(6)
	v_mfma_f32_16x16x32_bf16 v[20:23], v[40:43], v[20:23], v[24:27]
	v_add_f32_e32 v122, 1.0, v122
	v_rcp_f32_e32 v122, v122
	v_mov_b32_e32 v139, v134
	s_waitcnt vmcnt(5)
	v_mfma_f32_16x16x32_bf16 v[16:19], v[36:39], v[16:19], v[20:23]
	s_waitcnt vmcnt(4)
	v_mov_b32_e32 v29, v32
	v_pk_mul_f32 v[122:123], v[122:123], v[130:131]
	v_mov_b32_e32 v131, v54
	v_mul_f32_e32 v122, v122, v123
	v_mul_f32_e32 v123, 0xbfb8aa3b, v138
	v_exp_f32_e32 v123, v123
	s_waitcnt vmcnt(3)
	v_lshlrev_b32_e32 v20, 16, v120
	v_mul_f32_e32 v21, 0xbfb8aa3b, v20
	v_exp_f32_e32 v21, v21
	v_add_f32_e32 v123, 1.0, v123
	v_rcp_f32_e32 v130, v123
	v_and_b32_e32 v22, 0xffff0000, v120
	v_add_f32_e32 v21, 1.0, v21
	v_rcp_f32_e32 v28, v21
	v_mov_b32_e32 v21, v16
	v_mul_f32_e32 v16, 0xbfb8aa3b, v22
	v_pk_mul_f32 v[130:131], v[130:131], v[138:139]
	v_exp_f32_e32 v16, v16
	v_mul_f32_e32 v123, v130, v131
	v_mul_f32_e32 v130, 0xbfb8aa3b, v140
	v_exp_f32_e32 v130, v130
	v_pk_mul_f32 v[20:21], v[28:29], v[20:21]
	v_add_f32_e32 v16, 1.0, v16
	v_mul_f32_e32 v25, v20, v21
	v_rcp_f32_e32 v20, v16
	v_add_f32_e32 v130, 1.0, v130
	v_rcp_f32_e32 v130, v130
	v_mov_b32_e32 v21, v33
	v_mov_b32_e32 v23, v17
	v_lshlrev_b32_e32 v24, 16, v121
	v_pk_mul_f32 v[16:17], v[20:21], v[22:23]
	v_mov_b32_e32 v131, v55
	v_mov_b32_e32 v141, v135
	v_mul_f32_e32 v16, v16, v17
	v_mul_f32_e32 v17, 0xbfb8aa3b, v24
	v_pk_mul_f32 v[130:131], v[130:131], v[140:141]
	s_add_u32 s0, s6, s0
	v_exp_f32_e32 v17, v17
	v_mul_f32_e32 v130, v130, v131
	s_addc_u32 s1, s7, s1
	v_cvt_pk_bf16_f32 v122, v132, v122
	v_cvt_pk_bf16_f32 v123, v123, v130
	v_lshl_add_u64 v[130:131], s[0:1], 0, v[112:113]
	v_lshl_add_u64 v[130:131], v[130:131], 0, v[184:185]
	v_and_b32_e32 v26, 0xffff0000, v121
	global_store_dwordx2 v[130:131], v[122:123], off
	v_cvt_pk_bf16_f32 v16, v25, v16
	v_add_f32_e32 v17, 1.0, v17
	v_mov_b32_e32 v25, v18
	v_mul_f32_e32 v18, 0xbfb8aa3b, v26
	v_rcp_f32_e32 v20, v17
	v_exp_f32_e32 v18, v18
	v_mov_b32_e32 v21, v34
	v_mov_b32_e32 v27, v19
	v_pk_mul_f32 v[20:21], v[20:21], v[24:25]
	v_add_f32_e32 v18, 1.0, v18
	v_mul_f32_e32 v17, v20, v21
	v_rcp_f32_e32 v20, v18
	v_mov_b32_e32 v21, v35
	v_and_b32_e32 v22, 0xffff0000, v128
	v_mov_b32_e32 v29, v92
	v_pk_mul_f32 v[18:19], v[20:21], v[26:27]
	v_lshlrev_b32_e32 v20, 16, v128
	v_mul_f32_e32 v18, v18, v19
	v_cvt_pk_bf16_f32 v17, v17, v18
	v_lshl_add_u64 v[18:19], s[0:1], 0, v[114:115]
	v_lshl_add_u64 v[18:19], v[18:19], 0, v[184:185]
	global_store_dwordx2 v[18:19], v[16:17], off
	v_mfma_f32_16x16x32_bf16 v[16:19], v[108:111], v[12:15], 0
	v_mul_f32_e32 v21, 0xbfb8aa3b, v20
	v_exp_f32_e32 v21, v21
	v_lshlrev_b32_e32 v24, 16, v129
	v_mfma_f32_16x16x32_bf16 v[16:19], v[104:107], v[8:11], v[16:19]
	v_and_b32_e32 v26, 0xffff0000, v129
	v_add_f32_e32 v21, 1.0, v21
	v_rcp_f32_e32 v28, v21
	v_mfma_f32_16x16x32_bf16 v[16:19], v[100:103], v[4:7], v[16:19]
	s_add_u32 s0, s9, s11
	s_addc_u32 s1, s8, s20
	s_lshl_b64 s[0:1], s[0:1], 10
	v_mfma_f32_16x16x32_bf16 v[16:19], v[96:99], v[0:3], v[16:19]
	s_add_u32 s0, s6, s0
	s_addc_u32 s1, s7, s1
	s_nop 5
	v_mov_b32_e32 v21, v16
	v_mul_f32_e32 v16, 0xbfb8aa3b, v22
	v_exp_f32_e32 v16, v16
	v_mov_b32_e32 v23, v17
	v_mov_b32_e32 v25, v18
	v_mul_f32_e32 v18, 0xbfb8aa3b, v26
	v_add_f32_e32 v16, 1.0, v16
	v_rcp_f32_e32 v92, v16
	v_exp_f32_e32 v18, v18
	v_pk_mul_f32 v[20:21], v[28:29], v[20:21]
	v_mov_b32_e32 v27, v19
	v_pk_mul_f32 v[16:17], v[92:93], v[22:23]
	v_mul_f32_e32 v20, v20, v21
	v_mul_f32_e32 v16, v16, v17
	v_mul_f32_e32 v17, 0xbfb8aa3b, v24
	v_exp_f32_e32 v17, v17
	v_add_f32_e32 v18, 1.0, v18
	v_cvt_pk_bf16_f32 v16, v20, v16
	v_mov_b32_e32 v21, v94
	v_add_f32_e32 v17, 1.0, v17
	v_rcp_f32_e32 v20, v17
	v_rcp_f32_e32 v94, v18
	v_and_b32_e32 v22, 0xffff0000, v126
	v_mov_b32_e32 v29, v72
	v_pk_mul_f32 v[20:21], v[20:21], v[24:25]
	v_pk_mul_f32 v[18:19], v[94:95], v[26:27]
	v_mul_f32_e32 v17, v20, v21
	v_mul_f32_e32 v18, v18, v19
	v_cvt_pk_bf16_f32 v17, v17, v18
	v_lshl_add_u64 v[18:19], s[0:1], 0, v[112:113]
	v_lshl_add_u64 v[18:19], v[18:19], 0, v[184:185]
	global_store_dwordx2 v[18:19], v[16:17], off
	v_mfma_f32_16x16x32_bf16 v[16:19], v[88:91], v[12:15], 0
	v_lshlrev_b32_e32 v20, 16, v126
	v_mul_f32_e32 v21, 0xbfb8aa3b, v20
	v_exp_f32_e32 v21, v21
	v_mfma_f32_16x16x32_bf16 v[16:19], v[84:87], v[8:11], v[16:19]
	v_lshlrev_b32_e32 v24, 16, v127
	v_and_b32_e32 v26, 0xffff0000, v127
	v_add_f32_e32 v21, 1.0, v21
	v_mfma_f32_16x16x32_bf16 v[16:19], v[80:83], v[4:7], v[16:19]
	v_rcp_f32_e32 v28, v21
	v_mfma_f32_16x16x32_bf16 v[16:19], v[76:79], v[0:3], v[16:19]
	s_nop 7
	v_mov_b32_e32 v21, v16
	v_mul_f32_e32 v16, 0xbfb8aa3b, v22
	v_exp_f32_e32 v16, v16
	v_mov_b32_e32 v23, v17
	v_mov_b32_e32 v25, v18
	v_mul_f32_e32 v18, 0xbfb8aa3b, v26
	v_add_f32_e32 v16, 1.0, v16
	v_rcp_f32_e32 v72, v16
	v_exp_f32_e32 v18, v18
	v_pk_mul_f32 v[20:21], v[28:29], v[20:21]
	v_mov_b32_e32 v27, v19
	v_pk_mul_f32 v[16:17], v[72:73], v[22:23]
	v_mul_f32_e32 v20, v20, v21
	v_mul_f32_e32 v16, v16, v17
	v_mul_f32_e32 v17, 0xbfb8aa3b, v24
	v_exp_f32_e32 v17, v17
	v_add_f32_e32 v18, 1.0, v18
	v_cvt_pk_bf16_f32 v16, v20, v16
	v_mov_b32_e32 v21, v74
	v_add_f32_e32 v17, 1.0, v17
	v_rcp_f32_e32 v20, v17
	v_rcp_f32_e32 v74, v18
	v_and_b32_e32 v22, 0xffff0000, v124
	v_mov_b32_e32 v29, v52
	v_pk_mul_f32 v[20:21], v[20:21], v[24:25]
	v_pk_mul_f32 v[18:19], v[74:75], v[26:27]
	v_mul_f32_e32 v17, v20, v21
	v_mul_f32_e32 v18, v18, v19
	v_cvt_pk_bf16_f32 v17, v17, v18
	v_lshl_add_u64 v[18:19], s[0:1], 0, v[116:117]
	v_lshl_add_u64 v[18:19], v[18:19], 0, v[184:185]
	global_store_dwordx2 v[18:19], v[16:17], off
	v_mfma_f32_16x16x32_bf16 v[16:19], v[68:71], v[12:15], 0
	v_lshlrev_b32_e32 v20, 16, v124
	v_mul_f32_e32 v21, 0xbfb8aa3b, v20
	v_exp_f32_e32 v21, v21
	v_mfma_f32_16x16x32_bf16 v[16:19], v[64:67], v[8:11], v[16:19]
	v_lshlrev_b32_e32 v24, 16, v125
	v_and_b32_e32 v26, 0xffff0000, v125
	v_add_f32_e32 v21, 1.0, v21
	v_mfma_f32_16x16x32_bf16 v[12:15], v[48:51], v[12:15], 0
	v_rcp_f32_e32 v28, v21
	s_add_u32 s0, s9, s5
	s_addc_u32 s1, s8, s10
	v_mfma_f32_16x16x32_bf16 v[16:19], v[60:63], v[4:7], v[16:19]
	s_lshl_b64 s[0:1], s[0:1], 10
	s_add_u32 s0, s6, s0
	s_addc_u32 s1, s7, s1
	v_mfma_f32_16x16x32_bf16 v[8:11], v[44:47], v[8:11], v[12:15]
	s_cmp_lg_u32 s4, 0
	v_mfma_f32_16x16x32_bf16 v[16:19], v[56:59], v[0:3], v[16:19]
	s_nop 0
	v_mov_b32_e32 v13, v32
	v_mfma_f32_16x16x32_bf16 v[4:7], v[40:43], v[4:7], v[8:11]
	v_mfma_f32_16x16x32_bf16 v[0:3], v[36:39], v[0:3], v[4:7]
	s_nop 3
	v_mov_b32_e32 v21, v16
	v_mul_f32_e32 v16, 0xbfb8aa3b, v22
	v_exp_f32_e32 v16, v16
	s_waitcnt vmcnt(6)
	v_lshlrev_b32_e32 v4, 16, v118
	v_mul_f32_e32 v5, 0xbfb8aa3b, v4
	v_exp_f32_e32 v5, v5
	v_add_f32_e32 v16, 1.0, v16
	v_rcp_f32_e32 v52, v16
	v_and_b32_e32 v6, 0xffff0000, v118
	v_add_f32_e32 v5, 1.0, v5
	v_rcp_f32_e32 v12, v5
	v_mov_b32_e32 v5, v0
	v_mul_f32_e32 v0, 0xbfb8aa3b, v6
	v_mov_b32_e32 v23, v17
	v_exp_f32_e32 v0, v0
	v_pk_mul_f32 v[16:17], v[52:53], v[22:23]
	v_mov_b32_e32 v25, v18
	v_mul_f32_e32 v16, v16, v17
	v_mul_f32_e32 v17, 0xbfb8aa3b, v24
	v_mul_f32_e32 v18, 0xbfb8aa3b, v26
	v_exp_f32_e32 v17, v17
	v_exp_f32_e32 v18, v18
	v_add_f32_e32 v0, 1.0, v0
	v_rcp_f32_e32 v32, v0
	v_pk_mul_f32 v[20:21], v[28:29], v[20:21]
	v_add_f32_e32 v17, 1.0, v17
	v_mul_f32_e32 v20, v20, v21
	v_add_f32_e32 v18, 1.0, v18
	v_cvt_pk_bf16_f32 v16, v20, v16
	v_rcp_f32_e32 v20, v17
	v_mov_b32_e32 v21, v54
	v_rcp_f32_e32 v54, v18
	v_mov_b32_e32 v7, v1
	v_lshlrev_b32_e32 v8, 16, v119
	v_and_b32_e32 v10, 0xffff0000, v119
	v_pk_mul_f32 v[0:1], v[32:33], v[6:7]
	v_mov_b32_e32 v9, v2
	v_mul_f32_e32 v0, v0, v1
	v_mul_f32_e32 v1, 0xbfb8aa3b, v8
	v_mul_f32_e32 v2, 0xbfb8aa3b, v10
	v_mov_b32_e32 v27, v19
	v_exp_f32_e32 v1, v1
	v_exp_f32_e32 v2, v2
	v_pk_mul_f32 v[20:21], v[20:21], v[24:25]
	v_pk_mul_f32 v[18:19], v[54:55], v[26:27]
	v_mul_f32_e32 v17, v20, v21
	v_mul_f32_e32 v18, v18, v19
	v_cvt_pk_bf16_f32 v17, v17, v18
	v_lshl_add_u64 v[18:19], s[0:1], 0, v[112:113]
	v_pk_mul_f32 v[4:5], v[12:13], v[4:5]
	v_lshl_add_u64 v[18:19], v[18:19], 0, v[184:185]
	v_mul_f32_e32 v4, v4, v5
	v_add_f32_e32 v1, 1.0, v1
	v_add_f32_e32 v2, 1.0, v2
	global_store_dwordx2 v[18:19], v[16:17], off
	v_cvt_pk_bf16_f32 v0, v4, v0
	v_rcp_f32_e32 v4, v1
	v_mov_b32_e32 v5, v34
	v_rcp_f32_e32 v34, v2
	v_mov_b32_e32 v11, v3
	v_pk_mul_f32 v[4:5], v[4:5], v[8:9]
	v_pk_mul_f32 v[2:3], v[34:35], v[10:11]
	v_mul_f32_e32 v1, v4, v5
	v_mul_f32_e32 v2, v2, v3
	v_cvt_pk_bf16_f32 v1, v1, v2
	v_lshl_add_u64 v[2:3], s[0:1], 0, v[114:115]
	v_lshl_add_u64 v[2:3], v[2:3], 0, v[184:185]
	global_store_dwordx2 v[2:3], v[0:1], off
	v_cvt_f32_i32_e32 v0, s42
	s_mov_b64 s[0:1], -1
	s_barrier
	v_sub_f32_e32 v221, 0xc0a00000, v0
	s_cbranch_scc0 .LBB0_788
	v_cmp_gt_f32_e32 vcc, s75, v221
	s_bfe_u32 s4, s16, 0x40004
	s_and_b64 s[0:1], vcc, exec
	v_cndmask_b32_e32 v0, 0, v231, vcc
	v_add_f32_e32 v0, v221, v0
	v_exp_f32_e32 v0, v0
	s_cselect_b32 s0, 0xffffffc0, 0
	s_mov_b64 s[20:21], s[64:65]
	v_mov_b32_e32 v187, v197
	v_ldexp_f32 v0, v0, s0
	s_lshl_b32 s0, s42, 2
	s_add_i32 s0, s12, s0
	v_sub_f32_e32 v120, 1.0, v0
	v_lshl_add_u64 v[0:1], s[20:21], 0, v[186:187]
	s_mov_b64 s[6:7], 0x1a801000
	s_ashr_i32 s1, s0, 31
	v_lshl_add_u64 v[0:1], v[0:1], 0, s[6:7]
	s_lshl_b64 s[6:7], s[0:1], 10
	s_add_i32 s0, s0, 16
	s_ashr_i32 s1, s0, 31
	s_lshl_b64 s[0:1], s[0:1], 10
	s_ashr_i32 s5, s69, 4
	s_ashr_i32 s19, s18, 31
	v_lshl_add_u64 v[2:3], v[0:1], 0, s[6:7]
	v_lshl_add_u64 v[0:1], v[0:1], 0, s[0:1]
	s_add_u32 s0, s20, 0xee01000
	s_addc_u32 s1, s21, 0
	s_lshl_b32 s7, s4, 13
	s_lshl_b32 s8, s5, 17
	s_lshl_b32 s6, s42, 11
	s_or_b32 s7, s7, s8
	s_add_i32 s6, s7, s6
	s_ashr_i32 s7, s6, 31
	global_load_dwordx4 v[44:47], v[2:3], off nt
	global_load_dwordx4 v[48:51], v[2:3], off offset:1024 nt
	global_load_dwordx4 v[52:55], v[2:3], off offset:2048 nt
	global_load_dwordx4 v[56:59], v[2:3], off offset:3072 nt
	global_load_dwordx4 v[32:35], v[0:1], off nt
	global_load_dwordx4 v[20:23], v[0:1], off offset:1024 nt
	global_load_dwordx4 v[24:27], v[0:1], off offset:2048 nt
	global_load_dwordx4 v[28:31], v[0:1], off offset:3072 nt
	v_mov_b32_e32 v1, s7
	s_or_b32 s7, s6, 0x100
	s_ashr_i32 s8, s7, 31
	v_or_b32_e32 v0, s6, v220
	v_or_b32_e32 v16, s7, v220
	v_mov_b32_e32 v17, s8
	v_lshl_add_u64 v[12:13], v[0:1], 4, s[0:1]
	v_lshl_add_u64 v[60:61], v[16:17], 4, s[0:1]
	global_load_dwordx4 v[0:3], v[12:13], off
	global_load_dwordx4 v[4:7], v[12:13], off offset:1024
	global_load_dwordx4 v[8:11], v[12:13], off offset:2048
	s_nop 0
	global_load_dwordx4 v[12:15], v[12:13], off offset:3072
	s_nop 0
	global_load_dwordx4 v[16:19], v[60:61], off
	global_load_dwordx4 v[36:39], v[60:61], off offset:1024
	global_load_dwordx4 v[40:43], v[60:61], off offset:2048
	s_nop 0
	global_load_dwordx4 v[60:63], v[60:61], off offset:3072
	v_or_b32_e32 v239, 32, v208
	s_waitcnt vmcnt(7)
	v_mfma_f32_16x16x32_bf16 v[64:67], v[0:3], v[44:47], 0
	s_or_b32 s7, s6, 0x200
	s_ashr_i32 s8, s7, 31
	v_mfma_f32_16x16x32_bf16 v[0:3], v[0:3], v[32:35], 0
	s_waitcnt vmcnt(6)
	v_mfma_f32_16x16x32_bf16 v[64:67], v[4:7], v[48:51], v[64:67]
	v_mfma_f32_16x16x32_bf16 v[0:3], v[4:7], v[20:23], v[0:3]
	s_waitcnt vmcnt(5)
	v_mfma_f32_16x16x32_bf16 v[4:7], v[8:11], v[52:55], v[64:67]
	v_mfma_f32_16x16x32_bf16 v[0:3], v[8:11], v[24:27], v[0:3]
	s_waitcnt vmcnt(4)
	v_mfma_f32_16x16x32_bf16 v[8:11], v[12:15], v[56:59], v[4:7]
	v_mfma_f32_16x16x32_bf16 v[0:3], v[12:15], v[28:31], v[0:3]
	s_waitcnt vmcnt(3)
	v_mfma_f32_16x16x32_bf16 v[4:7], v[16:19], v[44:47], 0
	v_mfma_f32_16x16x32_bf16 v[12:15], v[16:19], v[32:35], 0
	s_waitcnt vmcnt(2)
	v_mfma_f32_16x16x32_bf16 v[4:7], v[36:39], v[48:51], v[4:7]
	v_mfma_f32_16x16x32_bf16 v[12:15], v[36:39], v[20:23], v[12:15]
	s_waitcnt vmcnt(1)
	v_mfma_f32_16x16x32_bf16 v[4:7], v[40:43], v[52:55], v[4:7]
	v_mfma_f32_16x16x32_bf16 v[16:19], v[40:43], v[24:27], v[12:15]
	s_waitcnt vmcnt(0)
	v_mfma_f32_16x16x32_bf16 v[12:15], v[60:63], v[56:59], v[4:7]
	v_mfma_f32_16x16x32_bf16 v[4:7], v[60:63], v[28:31], v[16:19]
	s_nop 4
	v_or_b32_e32 v16, s7, v220
	s_or_b32 s7, s6, 0x300
	v_mov_b32_e32 v17, s8
	s_ashr_i32 s8, s7, 31
	v_or_b32_e32 v64, s7, v220
	v_mov_b32_e32 v65, s8
	v_lshl_add_u64 v[60:61], v[16:17], 4, s[0:1]
	v_lshl_add_u64 v[76:77], v[64:65], 4, s[0:1]
	global_load_dwordx4 v[16:19], v[60:61], off
	global_load_dwordx4 v[36:39], v[60:61], off offset:1024
	global_load_dwordx4 v[40:43], v[60:61], off offset:2048
	s_nop 0
	global_load_dwordx4 v[60:63], v[60:61], off offset:3072
	s_nop 0
	global_load_dwordx4 v[64:67], v[76:77], off
	global_load_dwordx4 v[68:71], v[76:77], off offset:1024
	global_load_dwordx4 v[72:75], v[76:77], off offset:2048
	s_nop 0
	global_load_dwordx4 v[76:79], v[76:77], off offset:3072
	s_waitcnt vmcnt(7)
	v_mfma_f32_16x16x32_bf16 v[80:83], v[16:19], v[44:47], 0
	s_or_b32 s7, s6, 0x400
	s_ashr_i32 s8, s7, 31
	v_mfma_f32_16x16x32_bf16 v[16:19], v[16:19], v[32:35], 0
	s_waitcnt vmcnt(6)
	v_mfma_f32_16x16x32_bf16 v[80:83], v[36:39], v[48:51], v[80:83]
	v_mfma_f32_16x16x32_bf16 v[16:19], v[36:39], v[20:23], v[16:19]
	s_waitcnt vmcnt(5)
	v_mfma_f32_16x16x32_bf16 v[36:39], v[40:43], v[52:55], v[80:83]
	v_mfma_f32_16x16x32_bf16 v[16:19], v[40:43], v[24:27], v[16:19]
	s_waitcnt vmcnt(4)
	v_mfma_f32_16x16x32_bf16 v[40:43], v[60:63], v[56:59], v[36:39]
	v_mfma_f32_16x16x32_bf16 v[16:19], v[60:63], v[28:31], v[16:19]
	s_waitcnt vmcnt(3)
	v_mfma_f32_16x16x32_bf16 v[36:39], v[64:67], v[44:47], 0
	v_mfma_f32_16x16x32_bf16 v[60:63], v[64:67], v[32:35], 0
	s_waitcnt vmcnt(2)
	v_mfma_f32_16x16x32_bf16 v[36:39], v[68:71], v[48:51], v[36:39]
	v_mfma_f32_16x16x32_bf16 v[60:63], v[68:71], v[20:23], v[60:63]
	s_waitcnt vmcnt(1)
	v_mfma_f32_16x16x32_bf16 v[36:39], v[72:75], v[52:55], v[36:39]
	v_mfma_f32_16x16x32_bf16 v[64:67], v[72:75], v[24:27], v[60:63]
	s_waitcnt vmcnt(0)
	v_mfma_f32_16x16x32_bf16 v[60:63], v[76:79], v[56:59], v[36:39]
	v_mfma_f32_16x16x32_bf16 v[36:39], v[76:79], v[28:31], v[64:67]
	s_nop 4
	v_or_b32_e32 v64, s7, v220
	s_or_b32 s7, s6, 0x500
	v_mov_b32_e32 v65, s8
	s_ashr_i32 s8, s7, 31
	v_or_b32_e32 v80, s7, v220
	v_mov_b32_e32 v81, s8
	v_lshl_add_u64 v[76:77], v[64:65], 4, s[0:1]
	v_lshl_add_u64 v[92:93], v[80:81], 4, s[0:1]
	global_load_dwordx4 v[64:67], v[76:77], off
	global_load_dwordx4 v[68:71], v[76:77], off offset:1024
	global_load_dwordx4 v[72:75], v[76:77], off offset:2048
	s_nop 0
	global_load_dwordx4 v[76:79], v[76:77], off offset:3072
	s_nop 0
	global_load_dwordx4 v[80:83], v[92:93], off
	global_load_dwordx4 v[84:87], v[92:93], off offset:1024
	global_load_dwordx4 v[88:91], v[92:93], off offset:2048
	s_nop 0
	global_load_dwordx4 v[92:95], v[92:93], off offset:3072
	s_waitcnt vmcnt(7)
	v_mfma_f32_16x16x32_bf16 v[96:99], v[64:67], v[44:47], 0
	s_or_b32 s7, s6, 0x600
	s_or_b32 s6, s6, 0x700
	s_ashr_i32 s8, s7, 31
	v_mfma_f32_16x16x32_bf16 v[64:67], v[64:67], v[32:35], 0
	s_waitcnt vmcnt(6)
	v_mfma_f32_16x16x32_bf16 v[64:67], v[68:71], v[20:23], v[64:67]
	v_mfma_f32_16x16x32_bf16 v[96:99], v[68:71], v[48:51], v[96:99]
	s_waitcnt vmcnt(5)
	v_mfma_f32_16x16x32_bf16 v[64:67], v[72:75], v[24:27], v[64:67]
	v_mfma_f32_16x16x32_bf16 v[68:71], v[72:75], v[52:55], v[96:99]
	s_waitcnt vmcnt(4)
	v_mfma_f32_16x16x32_bf16 v[100:103], v[76:79], v[28:31], v[64:67]
	s_waitcnt vmcnt(3)
	v_mfma_f32_16x16x32_bf16 v[64:67], v[80:83], v[44:47], 0
	v_mfma_f32_16x16x32_bf16 v[96:99], v[76:79], v[56:59], v[68:71]
	v_mfma_f32_16x16x32_bf16 v[68:71], v[80:83], v[32:35], 0
	v_or_b32_e32 v80, s6, v220
	s_waitcnt vmcnt(2)
	v_mfma_f32_16x16x32_bf16 v[64:67], v[84:87], v[48:51], v[64:67]
	v_mfma_f32_16x16x32_bf16 v[68:71], v[84:87], v[20:23], v[68:71]
	s_waitcnt vmcnt(1)
	v_mfma_f32_16x16x32_bf16 v[64:67], v[88:91], v[52:55], v[64:67]
	v_mfma_f32_16x16x32_bf16 v[68:71], v[88:91], v[24:27], v[68:71]
	s_waitcnt vmcnt(0)
	v_mfma_f32_16x16x32_bf16 v[84:87], v[92:95], v[56:59], v[64:67]
	s_nop 4
	v_or_b32_e32 v64, s7, v220
	s_ashr_i32 s7, s6, 31
	v_mov_b32_e32 v65, s8
	v_mov_b32_e32 v81, s7
	v_lshl_add_u64 v[76:77], v[64:65], 4, s[0:1]
	v_lshl_add_u64 v[108:109], v[80:81], 4, s[0:1]
	v_mfma_f32_16x16x32_bf16 v[104:107], v[92:95], v[28:31], v[68:71]
	global_load_dwordx4 v[64:67], v[76:77], off
	s_nop 1
	global_load_dwordx4 v[68:71], v[76:77], off offset:1024
	global_load_dwordx4 v[72:75], v[76:77], off offset:2048
	s_nop 0
	global_load_dwordx4 v[76:79], v[76:77], off offset:3072
	s_nop 0
	global_load_dwordx4 v[80:83], v[108:109], off
	global_load_dwordx4 v[88:91], v[108:109], off offset:1024
	global_load_dwordx4 v[92:95], v[108:109], off offset:2048
	s_nop 0
	global_load_dwordx4 v[108:111], v[108:109], off offset:3072
	s_waitcnt vmcnt(7)
	v_mfma_f32_16x16x32_bf16 v[112:115], v[64:67], v[44:47], 0
	v_cmp_gt_f32_e32 vcc, s15, v120
	s_and_b64 s[0:1], vcc, exec
	s_cselect_b32 s0, 32, 0
	v_mfma_f32_16x16x32_bf16 v[64:67], v[64:67], v[32:35], 0
	s_or_b32 s6, s68, 64
	s_lshl_b32 s1, s42, 4
	s_ashr_i32 s43, s42, 31
	s_waitcnt vmcnt(6)
	v_mfma_f32_16x16x32_bf16 v[64:67], v[68:71], v[20:23], v[64:67]
	s_lshl_b64 s[10:11], s[42:43], 12
	v_mov_b32_e32 v189, v197
	v_mfma_f32_16x16x32_bf16 v[112:115], v[68:71], v[48:51], v[112:115]
	s_waitcnt vmcnt(5)
	v_mfma_f32_16x16x32_bf16 v[64:67], v[72:75], v[24:27], v[64:67]
	v_mfma_f32_16x16x32_bf16 v[68:71], v[72:75], v[52:55], v[112:115]
	s_waitcnt vmcnt(4)
	v_mfma_f32_16x16x32_bf16 v[116:119], v[76:79], v[28:31], v[64:67]
	s_waitcnt vmcnt(3)
	v_mfma_f32_16x16x32_bf16 v[64:67], v[80:83], v[44:47], 0
	v_mfma_f32_16x16x32_bf16 v[112:115], v[76:79], v[56:59], v[68:71]
	v_mfma_f32_16x16x32_bf16 v[68:71], v[80:83], v[32:35], 0
	s_waitcnt vmcnt(2)
	v_mfma_f32_16x16x32_bf16 v[64:67], v[88:91], v[48:51], v[64:67]
	v_mfma_f32_16x16x32_bf16 v[68:71], v[88:91], v[20:23], v[68:71]
	s_waitcnt vmcnt(1)
	v_mfma_f32_16x16x32_bf16 v[64:67], v[92:95], v[52:55], v[64:67]
	v_mfma_f32_16x16x32_bf16 v[68:71], v[92:95], v[24:27], v[68:71]
	s_waitcnt vmcnt(0)
	v_mfma_f32_16x16x32_bf16 v[92:95], v[108:111], v[56:59], v[64:67]
	s_nop 4
	v_ldexp_f32 v64, v120, s0
	v_log_f32_e32 v64, v64
	v_cndmask_b32_e32 v65, 0, v232, vcc
	s_lshl_b32 s0, s5, 6
	s_add_i32 s1, s1, s0
	v_sub_f32_e32 v185, v64, v65
	v_add3_u32 v64, v206, s6, 1
	v_cvt_f32_u32_e32 v64, v64
	s_or_b32 s0, s1, s4
	v_lshl_or_b32 v190, s0, 9, v206
	s_lshl_b64 s[0:1], s[18:19], 10
	v_mul_f32_e32 v64, v185, v64
	v_exp_f32_e32 v120, v64
	s_add_u32 s0, s20, s0
	s_addc_u32 s1, s21, s1
	s_add_u32 s0, s0, 0x1b801000
	v_pk_mul_f32 v[64:65], v[120:121], v[8:9] op_sel_hi:[0,1]
	v_add_u32_e32 v8, s68, v206
	v_add_u32_e32 v8, 0x51, v8
	v_cvt_f32_ubyte0_e32 v8, v8
	v_mul_f32_e32 v8, v185, v8
	s_addc_u32 s1, s1, 0
	v_mfma_f32_16x16x32_bf16 v[108:111], v[108:111], v[28:31], v[68:71]
	v_mul_f32_e64 v76, v120, v60
	v_mul_f32_e64 v77, v120, v61
	v_exp_f32_e32 v60, v8
	s_add_u32 s4, s0, s10
	s_addc_u32 s5, s1, s11
	v_lshl_add_u64 v[204:205], s[4:5], 0, v[186:187]
	v_pk_mul_f32 v[82:83], v[120:121], v[98:99] op_sel_hi:[0,1]
	v_add_co_u32_e32 v98, vcc, s71, v204
	v_pk_mul_f32 v[66:67], v[120:121], v[10:11] op_sel_hi:[0,1]
	v_pk_mul_f32 v[70:71], v[120:121], v[14:15] op_sel_hi:[0,1]
	v_pk_mul_f32 v[68:69], v[120:121], v[12:13] op_sel_hi:[0,1]
	v_pk_mul_f32 v[74:75], v[120:121], v[42:43] op_sel_hi:[0,1]
	v_pk_mul_f32 v[72:73], v[120:121], v[40:41] op_sel_hi:[0,1]
	v_pk_mul_f32 v[78:79], v[120:121], v[62:63] op_sel_hi:[0,1]
	v_pk_mul_f32 v[80:81], v[120:121], v[96:97] op_sel_hi:[0,1]
	v_pk_mul_f32 v[88:89], v[120:121], v[112:113] op_sel_hi:[0,1]
	v_pk_mul_f32 v[2:3], v[60:61], v[2:3] op_sel_hi:[0,1]
	v_pk_mul_f32 v[0:1], v[60:61], v[0:1] op_sel_hi:[0,1]
	v_pk_mul_f32 v[6:7], v[60:61], v[6:7] op_sel_hi:[0,1]
	v_pk_mul_f32 v[4:5], v[60:61], v[4:5] op_sel_hi:[0,1]
	v_pk_mul_f32 v[10:11], v[60:61], v[18:19] op_sel_hi:[0,1]
	v_pk_mul_f32 v[8:9], v[60:61], v[16:17] op_sel_hi:[0,1]
	v_pk_mul_f32 v[14:15], v[60:61], v[38:39] op_sel_hi:[0,1]
	v_pk_mul_f32 v[12:13], v[60:61], v[36:37] op_sel_hi:[0,1]
	v_pk_mul_f32 v[18:19], v[60:61], v[102:103] op_sel_hi:[0,1]
	v_pk_mul_f32 v[16:17], v[60:61], v[100:101] op_sel_hi:[0,1]
	v_pk_mul_f32 v[38:39], v[60:61], v[106:107] op_sel_hi:[0,1]
	v_pk_mul_f32 v[36:37], v[60:61], v[104:105] op_sel_hi:[0,1]
	v_pk_mul_f32 v[42:43], v[60:61], v[118:119] op_sel_hi:[0,1]
	v_pk_mul_f32 v[40:41], v[60:61], v[116:117] op_sel_hi:[0,1]
	v_pk_mul_f32 v[62:63], v[60:61], v[110:111] op_sel_hi:[0,1]
	v_pk_mul_f32 v[60:61], v[60:61], v[108:109] op_sel_hi:[0,1]
	v_lshl_add_u64 v[96:97], s[20:21], 0, v[188:189]
	global_load_dwordx4 v[144:147], v186, s[4:5]
	global_load_dwordx4 v[148:151], v186, s[4:5] offset:1024
	global_load_dwordx4 v[152:155], v186, s[4:5] offset:2048
	global_load_dwordx4 v[156:159], v186, s[4:5] offset:3072
	s_mov_b64 s[4:5], 0x4000
	v_addc_co_u32_e32 v99, vcc, 0, v205, vcc
	v_or_b32_e32 v100, 16, v190
	v_or_b32_e32 v104, 32, v190
	v_or_b32_e32 v108, 48, v190
	v_or_b32_e32 v112, 64, v190
	v_or_b32_e32 v124, 0x50, v190
	v_or_b32_e32 v132, 0x60, v190
	v_or_b32_e32 v140, 0x70, v190
	v_pk_mul_f32 v[86:87], v[120:121], v[86:87] op_sel_hi:[0,1]
	v_pk_mul_f32 v[84:85], v[120:121], v[84:85] op_sel_hi:[0,1]
	v_pk_mul_f32 v[90:91], v[120:121], v[114:115] op_sel_hi:[0,1]
	v_pk_mul_f32 v[94:95], v[120:121], v[94:95] op_sel_hi:[0,1]
	v_pk_mul_f32 v[92:93], v[120:121], v[92:93] op_sel_hi:[0,1]
	v_lshl_add_u64 v[202:203], v[96:97], 0, s[58:59]
	v_lshl_add_u64 v[96:97], v[204:205], 0, s[4:5]
	global_load_dwordx4 v[136:139], v[98:99], off
	global_load_dwordx4 v[128:131], v[96:97], off offset:1024
	global_load_dwordx4 v[116:119], v[96:97], off offset:2048
	global_load_dwordx4 v[120:123], v[96:97], off offset:3072
	v_ashrrev_i32_e32 v191, 31, v190
	v_ashrrev_i32_e32 v101, 31, v100
	v_ashrrev_i32_e32 v105, 31, v104
	v_ashrrev_i32_e32 v109, 31, v108
	v_ashrrev_i32_e32 v113, 31, v112
	v_ashrrev_i32_e32 v125, 31, v124
	v_ashrrev_i32_e32 v133, 31, v132
	v_ashrrev_i32_e32 v141, 31, v140
	v_lshlrev_b64 v[96:97], 6, v[190:191]
	v_lshlrev_b64 v[100:101], 6, v[100:101]
	v_lshlrev_b64 v[104:105], 6, v[104:105]
	v_lshlrev_b64 v[108:109], 6, v[108:109]
	v_lshlrev_b64 v[112:113], 6, v[112:113]
	v_lshlrev_b64 v[124:125], 6, v[124:125]
	v_lshlrev_b64 v[132:133], 6, v[132:133]
	v_lshlrev_b64 v[140:141], 6, v[140:141]
	v_lshl_add_u64 v[96:97], v[202:203], 0, v[96:97]
	v_lshl_add_u64 v[100:101], v[202:203], 0, v[100:101]
	v_lshl_add_u64 v[104:105], v[202:203], 0, v[104:105]
	v_lshl_add_u64 v[108:109], v[202:203], 0, v[108:109]
	v_lshl_add_u64 v[112:113], v[202:203], 0, v[112:113]
	v_lshl_add_u64 v[124:125], v[202:203], 0, v[124:125]
	v_lshl_add_u64 v[132:133], v[202:203], 0, v[132:133]
	v_lshl_add_u64 v[140:141], v[202:203], 0, v[140:141]
	global_load_dwordx4 v[96:99], v[96:97], off
	s_nop 0
	global_load_dwordx4 v[100:103], v[100:101], off
	s_nop 0
	global_load_dwordx4 v[104:107], v[104:105], off
	s_nop 0
	global_load_dwordx4 v[108:111], v[108:109], off
	s_nop 0
	global_load_dwordx4 v[112:115], v[112:113], off
	s_nop 0
	global_load_dwordx4 v[124:127], v[124:125], off
	s_nop 0
	global_load_dwordx4 v[132:135], v[132:133], off
	s_nop 0
	global_load_dwordx4 v[140:143], v[140:141], off
	s_waitcnt vmcnt(15)
	v_mfma_f32_16x16x32_bf16 v[160:163], v[144:147], v[44:47], 0
	v_or_b32_e32 v191, s6, v206
	v_sub_u32_e32 v164, v191, v208
	v_cvt_f32_ubyte0_e32 v164, v164
	s_waitcnt vmcnt(14)
	v_mfma_f32_16x16x32_bf16 v[160:163], v[148:151], v[48:51], v[160:163]
	v_mul_f32_e32 v164, v185, v164
	v_exp_f32_e32 v164, v164
	v_or_b32_e32 v189, 0x50, v212
	s_waitcnt vmcnt(13)
	v_mfma_f32_16x16x32_bf16 v[160:163], v[152:155], v[52:55], v[160:163]
	v_sub_u32_e32 v166, v191, v213
	v_cvt_f32_ubyte0_e32 v166, v166
	v_mul_f32_e32 v166, v185, v166
	s_waitcnt vmcnt(12)
	v_mfma_f32_16x16x32_bf16 v[160:163], v[156:159], v[56:59], v[160:163]
	v_exp_f32_e32 v166, v166
	s_mov_b64 s[4:5], 0x8000
	v_mfma_f32_16x16x32_bf16 v[144:147], v[144:147], v[32:35], 0
	v_mfma_f32_16x16x32_bf16 v[144:147], v[148:151], v[20:23], v[144:147]
	s_nop 3
	v_mul_f32_e32 v160, v164, v160
	v_add_u32_e32 v164, v191, v219
	v_cvt_f32_ubyte0_e32 v164, v164
	v_mul_f32_e32 v164, v185, v164
	v_exp_f32_e32 v164, v164
	v_mfma_f32_16x16x32_bf16 v[144:147], v[152:155], v[24:27], v[144:147]
	v_sub_u32_e32 v148, v189, v208
	v_cvt_f32_ubyte0_e32 v148, v148
	v_mul_f32_e32 v161, v164, v161
	v_sub_u32_e32 v164, v191, v218
	v_cvt_f32_ubyte0_e32 v164, v164
	v_mul_f32_e32 v164, v185, v164
	v_exp_f32_e32 v164, v164
	v_cvt_pk_bf16_f32 v160, v160, v161
	v_mul_f32_e32 v148, v185, v148
	v_mfma_f32_16x16x32_bf16 v[144:147], v[156:159], v[28:31], v[144:147]
	v_mul_f32_e32 v162, v164, v162
	v_sub_u32_e32 v164, v191, v217
	v_cvt_f32_ubyte0_e32 v164, v164
	v_mul_f32_e32 v164, v185, v164
	v_exp_f32_e32 v164, v164
	v_exp_f32_e32 v148, v148
	v_mul_f32_e32 v163, v164, v163
	v_cvt_pk_bf16_f32 v161, v162, v163
	s_waitcnt vmcnt(11)
	v_mfma_f32_16x16x32_bf16 v[162:165], v[136:139], v[44:47], 0
	v_mul_f32_e32 v144, v148, v144
	v_add_u32_e32 v148, v189, v219
	v_cvt_f32_ubyte0_e32 v148, v148
	v_mfma_f32_16x16x32_bf16 v[136:139], v[136:139], v[32:35], 0
	v_mul_f32_e32 v148, v185, v148
	v_exp_f32_e32 v148, v148
	s_waitcnt vmcnt(10)
	v_mfma_f32_16x16x32_bf16 v[162:165], v[128:131], v[48:51], v[162:165]
	v_mul_f32_e32 v145, v148, v145
	v_sub_u32_e32 v148, v189, v218
	v_mfma_f32_16x16x32_bf16 v[128:131], v[128:131], v[20:23], v[136:139]
	v_cvt_f32_ubyte0_e32 v148, v148
	v_mul_f32_e32 v148, v185, v148
	v_exp_f32_e32 v148, v148
	s_waitcnt vmcnt(9)
	v_mfma_f32_16x16x32_bf16 v[162:165], v[116:119], v[52:55], v[162:165]
	v_mul_f32_e32 v146, v148, v146
	v_mfma_f32_16x16x32_bf16 v[116:119], v[116:119], v[24:27], v[128:131]
	v_sub_u32_e32 v148, v189, v217
	v_cvt_f32_ubyte0_e32 v148, v148
	v_mul_f32_e32 v148, v185, v148
	s_waitcnt vmcnt(8)
	v_mfma_f32_16x16x32_bf16 v[162:165], v[120:123], v[56:59], v[162:165]
	v_exp_f32_e32 v148, v148
	s_nop 0
	v_mul_f32_e32 v147, v148, v147
	v_mfma_f32_16x16x32_bf16 v[116:119], v[120:123], v[28:31], v[116:119]
	v_sub_u32_e32 v120, v189, v213
	v_cvt_f32_ubyte0_e32 v120, v120
	v_mul_f32_e32 v120, v185, v120
	v_exp_f32_e32 v120, v120
	v_mul_f32_e32 v162, v166, v162
	v_sub_u32_e32 v166, v191, v216
	v_cvt_f32_ubyte0_e32 v166, v166
	s_nop 0
	v_mul_f32_e32 v116, v120, v116
	v_sub_u32_e32 v120, v189, v216
	v_cvt_f32_ubyte0_e32 v120, v120
	v_mul_f32_e32 v166, v185, v166
	v_mul_f32_e32 v120, v185, v120
	v_exp_f32_e32 v166, v166
	v_exp_f32_e32 v120, v120
	v_mul_f32_e32 v163, v166, v163
	v_sub_u32_e32 v166, v191, v215
	v_mul_f32_e32 v117, v120, v117
	v_sub_u32_e32 v120, v189, v215
	v_cvt_f32_ubyte0_e32 v166, v166
	v_cvt_f32_ubyte0_e32 v120, v120
	v_mul_f32_e32 v166, v185, v166
	v_mul_f32_e32 v120, v185, v120
	v_exp_f32_e32 v166, v166
	v_exp_f32_e32 v120, v120
	v_cvt_pk_bf16_f32 v162, v162, v163
	v_mul_f32_e32 v164, v166, v164
	v_sub_u32_e32 v166, v191, v214
	v_mul_f32_e32 v118, v120, v118
	v_sub_u32_e32 v120, v189, v214
	v_cvt_f32_ubyte0_e32 v166, v166
	v_cvt_f32_ubyte0_e32 v120, v120
	v_mul_f32_e32 v166, v185, v166
	v_mul_f32_e32 v120, v185, v120
	v_exp_f32_e32 v166, v166
	v_exp_f32_e32 v120, v120
	v_mul_f32_e32 v165, v166, v165
	v_cvt_pk_bf16_f32 v163, v164, v165
	v_cvt_pk_bf16_f32 v144, v144, v145
	v_cvt_pk_bf16_f32 v145, v146, v147
	v_mul_f32_e32 v119, v120, v119
	s_waitcnt vmcnt(7)
	v_mfma_f32_16x16x32_bf16 v[64:67], v[96:99], v[160:163], v[64:67]
	v_cvt_pk_bf16_f32 v146, v116, v117
	v_cvt_pk_bf16_f32 v147, v118, v119
	s_nop 0
	v_mfma_f32_16x16x32_bf16 v[0:3], v[96:99], v[144:147], v[0:3]
	s_waitcnt vmcnt(3)
	v_mfma_f32_16x16x32_bf16 v[96:99], v[112:115], v[144:147], v[16:19]
	s_nop 2
	v_add_co_u32_e32 v18, vcc, s73, v204
	v_lshl_add_u64 v[16:17], v[204:205], 0, s[4:5]
	s_nop 0
	v_addc_co_u32_e32 v19, vcc, 0, v205, vcc
	s_mov_b64 s[4:5], 0xc000
	global_load_dwordx4 v[168:171], v[18:19], off
	global_load_dwordx4 v[172:175], v[16:17], off offset:1024
	global_load_dwordx4 v[176:179], v[16:17], off offset:2048
	global_load_dwordx4 v[180:183], v[16:17], off offset:3072
	v_lshl_add_u64 v[16:17], v[204:205], 0, s[4:5]
	s_mov_b32 s4, 0xc000
	v_add_co_u32_e32 v18, vcc, s4, v204
	v_mfma_f32_16x16x32_bf16 v[76:79], v[108:111], v[160:163], v[76:79]
	s_nop 0
	v_addc_co_u32_e32 v19, vcc, 0, v205, vcc
	s_waitcnt vmcnt(4)
	v_mfma_f32_16x16x32_bf16 v[92:95], v[140:143], v[160:163], v[92:95]
	v_mfma_f32_16x16x32_bf16 v[12:15], v[108:111], v[144:147], v[12:15]
	v_mfma_f32_16x16x32_bf16 v[108:111], v[140:143], v[144:147], v[60:63]
	global_load_dwordx4 v[164:167], v[18:19], off
	global_load_dwordx4 v[156:159], v[16:17], off offset:1024
	global_load_dwordx4 v[148:151], v[16:17], off offset:2048
	global_load_dwordx4 v[140:143], v[16:17], off offset:3072
	v_or_b32_e32 v16, 0x80, v190
	v_ashrrev_i32_e32 v17, 31, v16
	v_lshlrev_b64 v[16:17], 6, v[16:17]
	v_lshl_add_u64 v[16:17], v[202:203], 0, v[16:17]
	global_load_dwordx4 v[120:123], v[16:17], off
	v_or_b32_e32 v16, 0x90, v190
	v_ashrrev_i32_e32 v17, 31, v16
	v_lshlrev_b64 v[16:17], 6, v[16:17]
	v_lshl_add_u64 v[16:17], v[202:203], 0, v[16:17]
	v_mfma_f32_16x16x32_bf16 v[68:71], v[100:103], v[160:163], v[68:71]
	v_mfma_f32_16x16x32_bf16 v[84:87], v[124:127], v[160:163], v[84:87]
	v_mfma_f32_16x16x32_bf16 v[4:7], v[100:103], v[144:147], v[4:7]
	v_mfma_f32_16x16x32_bf16 v[100:103], v[124:127], v[144:147], v[36:39]
	global_load_dwordx4 v[124:127], v[16:17], off
	v_or_b32_e32 v16, 0xa0, v190
	v_ashrrev_i32_e32 v17, 31, v16
	v_lshlrev_b64 v[16:17], 6, v[16:17]
	v_lshl_add_u64 v[16:17], v[202:203], 0, v[16:17]
	global_load_dwordx4 v[128:131], v[16:17], off
	v_or_b32_e32 v16, 0xb0, v190
	v_ashrrev_i32_e32 v17, 31, v16
	v_lshlrev_b64 v[16:17], 6, v[16:17]
	v_lshl_add_u64 v[16:17], v[202:203], 0, v[16:17]
	v_mfma_f32_16x16x32_bf16 v[72:75], v[104:107], v[160:163], v[72:75]
	v_mfma_f32_16x16x32_bf16 v[88:91], v[132:135], v[160:163], v[88:91]
	v_mfma_f32_16x16x32_bf16 v[8:11], v[104:107], v[144:147], v[8:11]
	v_mfma_f32_16x16x32_bf16 v[104:107], v[132:135], v[144:147], v[40:43]
	global_load_dwordx4 v[132:135], v[16:17], off
	v_or_b32_e32 v16, 0xc0, v190
	v_ashrrev_i32_e32 v17, 31, v16
	v_lshlrev_b64 v[16:17], 6, v[16:17]
	v_lshl_add_u64 v[16:17], v[202:203], 0, v[16:17]
	global_load_dwordx4 v[136:139], v[16:17], off
	v_or_b32_e32 v16, 0xd0, v190
	v_ashrrev_i32_e32 v17, 31, v16
	v_lshlrev_b64 v[16:17], 6, v[16:17]
	v_lshl_add_u64 v[16:17], v[202:203], 0, v[16:17]
	global_load_dwordx4 v[144:147], v[16:17], off
	v_or_b32_e32 v16, 0xe0, v190
	v_ashrrev_i32_e32 v17, 31, v16
	v_lshlrev_b64 v[16:17], 6, v[16:17]
	v_lshl_add_u64 v[16:17], v[202:203], 0, v[16:17]
	global_load_dwordx4 v[152:155], v[16:17], off
	v_or_b32_e32 v16, 0xf0, v190
	v_ashrrev_i32_e32 v17, 31, v16
	v_lshlrev_b64 v[16:17], 6, v[16:17]
	v_lshl_add_u64 v[16:17], v[202:203], 0, v[16:17]
	v_mfma_f32_16x16x32_bf16 v[80:83], v[112:115], v[160:163], v[80:83]
	global_load_dwordx4 v[160:163], v[16:17], off
	s_waitcnt vmcnt(15)
	v_mfma_f32_16x16x32_bf16 v[16:19], v[168:171], v[44:47], 0
	v_sub_u32_e32 v36, v191, v239
	v_cvt_f32_ubyte0_e32 v36, v36
	v_mul_f32_e32 v36, v185, v36
	s_waitcnt vmcnt(14)
	v_mfma_f32_16x16x32_bf16 v[16:19], v[172:175], v[48:51], v[16:19]
	v_exp_f32_e32 v36, v36
	v_or_b32_e32 v240, 33, v208
	v_or_b32_e32 v241, 34, v208
	s_waitcnt vmcnt(13)
	v_mfma_f32_16x16x32_bf16 v[16:19], v[176:179], v[52:55], v[16:19]
	v_or_b32_e32 v242, 35, v208
	v_or_b32_e32 v243, 49, v208
	v_or_b32_e32 v244, 50, v208
	s_waitcnt vmcnt(12)
	v_mfma_f32_16x16x32_bf16 v[16:19], v[180:183], v[56:59], v[16:19]
	v_or_b32_e32 v245, 51, v208
	s_mov_b64 s[4:5], 0x10000
	s_nop 5
	v_mul_f32_e32 v16, v36, v16
	v_sub_u32_e32 v36, v191, v240
	v_cvt_f32_ubyte0_e32 v36, v36
	v_mul_f32_e32 v36, v185, v36
	v_exp_f32_e32 v36, v36
	s_nop 0
	v_mul_f32_e32 v17, v36, v17
	v_sub_u32_e32 v36, v191, v241
	v_cvt_f32_ubyte0_e32 v36, v36
	v_mul_f32_e32 v36, v185, v36
	v_exp_f32_e32 v36, v36
	v_cvt_pk_bf16_f32 v116, v16, v17
	s_nop 0
	v_mul_f32_e32 v18, v36, v18
	v_sub_u32_e32 v36, v191, v242
	v_cvt_f32_ubyte0_e32 v36, v36
	v_mul_f32_e32 v36, v185, v36
	v_exp_f32_e32 v36, v36
	s_nop 0
	v_mul_f32_e32 v19, v36, v19
	v_cvt_pk_bf16_f32 v117, v18, v19
	s_waitcnt vmcnt(11)
	v_mfma_f32_16x16x32_bf16 v[16:19], v[164:167], v[44:47], 0
	v_sub_u32_e32 v36, v191, v222
	v_cvt_f32_ubyte0_e32 v36, v36
	v_mul_f32_e32 v36, v185, v36
	s_waitcnt vmcnt(10)
	v_mfma_f32_16x16x32_bf16 v[16:19], v[156:159], v[48:51], v[16:19]
	v_exp_f32_e32 v36, v36
	s_waitcnt vmcnt(9)
	v_mfma_f32_16x16x32_bf16 v[16:19], v[148:151], v[52:55], v[16:19]
	s_waitcnt vmcnt(8)
	v_mfma_f32_16x16x32_bf16 v[16:19], v[140:143], v[56:59], v[16:19]
	s_nop 7
	v_mul_f32_e32 v16, v36, v16
	v_sub_u32_e32 v36, v191, v243
	v_cvt_f32_ubyte0_e32 v36, v36
	v_mul_f32_e32 v36, v185, v36
	v_exp_f32_e32 v36, v36
	s_nop 0
	v_mul_f32_e32 v17, v36, v17
	v_sub_u32_e32 v36, v191, v244
	v_cvt_f32_ubyte0_e32 v36, v36
	v_mul_f32_e32 v36, v185, v36
	v_exp_f32_e32 v36, v36
	v_cvt_pk_bf16_f32 v118, v16, v17
	s_nop 0
	v_mul_f32_e32 v18, v36, v18
	v_sub_u32_e32 v36, v191, v245
	v_cvt_f32_ubyte0_e32 v36, v36
	v_mul_f32_e32 v36, v185, v36
	v_exp_f32_e32 v36, v36
	s_nop 0
	v_mul_f32_e32 v19, v36, v19
	v_cvt_pk_bf16_f32 v119, v18, v19
	s_waitcnt vmcnt(5)
	v_mfma_f32_16x16x32_bf16 v[40:43], v[128:131], v[116:119], v[72:75]
	v_mfma_f32_16x16x32_bf16 v[72:75], v[168:171], v[32:35], 0
	v_mfma_f32_16x16x32_bf16 v[72:75], v[172:175], v[20:23], v[72:75]
	v_mfma_f32_16x16x32_bf16 v[72:75], v[176:179], v[24:27], v[72:75]
	s_waitcnt vmcnt(4)
	v_mfma_f32_16x16x32_bf16 v[60:63], v[132:135], v[116:119], v[76:79]
	s_nop 2
	v_sub_u32_e32 v76, v189, v239
	v_cvt_f32_ubyte0_e32 v76, v76
	v_mul_f32_e32 v76, v185, v76
	v_mfma_f32_16x16x32_bf16 v[72:75], v[180:183], v[28:31], v[72:75]
	v_exp_f32_e32 v76, v76
	v_sub_u32_e32 v78, v189, v222
	v_cvt_f32_ubyte0_e32 v78, v78
	v_mul_f32_e32 v78, v185, v78
	v_exp_f32_e32 v78, v78
	s_nop 2
	v_mul_f32_e32 v72, v76, v72
	v_sub_u32_e32 v76, v189, v240
	v_cvt_f32_ubyte0_e32 v76, v76
	v_mul_f32_e32 v76, v185, v76
	v_exp_f32_e32 v76, v76
	v_mfma_f32_16x16x32_bf16 v[16:19], v[120:123], v[116:119], v[64:67]
	v_mul_f32_e32 v73, v76, v73
	v_sub_u32_e32 v76, v189, v241
	v_cvt_f32_ubyte0_e32 v76, v76
	v_mul_f32_e32 v76, v185, v76
	v_exp_f32_e32 v76, v76
	v_cvt_pk_bf16_f32 v72, v72, v73
	v_mfma_f32_16x16x32_bf16 v[36:39], v[124:127], v[116:119], v[68:71]
	v_mul_f32_e32 v74, v76, v74
	v_sub_u32_e32 v76, v189, v242
	v_cvt_f32_ubyte0_e32 v76, v76
	v_mul_f32_e32 v76, v185, v76
	v_exp_f32_e32 v76, v76
	s_waitcnt vmcnt(3)
	v_mfma_f32_16x16x32_bf16 v[64:67], v[136:139], v[116:119], v[80:83]
	v_mul_f32_e32 v75, v76, v75
	v_cvt_pk_bf16_f32 v73, v74, v75
	v_mfma_f32_16x16x32_bf16 v[74:77], v[164:167], v[32:35], 0
	s_nop 0
	v_mfma_f32_16x16x32_bf16 v[74:77], v[156:159], v[20:23], v[74:77]
	v_mfma_f32_16x16x32_bf16 v[74:77], v[148:151], v[24:27], v[74:77]
	v_mfma_f32_16x16x32_bf16 v[74:77], v[140:143], v[28:31], v[74:77]
	s_waitcnt vmcnt(2)
	v_mfma_f32_16x16x32_bf16 v[68:71], v[144:147], v[116:119], v[84:87]
	s_waitcnt vmcnt(1)
	v_mfma_f32_16x16x32_bf16 v[112:115], v[152:155], v[116:119], v[88:91]
	s_nop 3
	v_mul_f32_e32 v74, v78, v74
	v_sub_u32_e32 v78, v189, v243
	v_cvt_f32_ubyte0_e32 v78, v78
	v_mul_f32_e32 v78, v185, v78
	v_exp_f32_e32 v78, v78
	s_waitcnt vmcnt(0)
	v_mfma_f32_16x16x32_bf16 v[116:119], v[160:163], v[116:119], v[92:95]
	v_mul_f32_e32 v75, v78, v75
	v_sub_u32_e32 v78, v189, v244
	v_cvt_f32_ubyte0_e32 v78, v78
	v_mul_f32_e32 v78, v185, v78
	v_exp_f32_e32 v78, v78
	v_cvt_pk_bf16_f32 v74, v74, v75
	s_nop 0
	v_mul_f32_e32 v76, v78, v76
	v_sub_u32_e32 v78, v189, v245
	v_cvt_f32_ubyte0_e32 v78, v78
	v_mul_f32_e32 v78, v185, v78
	v_exp_f32_e32 v78, v78
	s_nop 0
	v_mul_f32_e32 v77, v78, v77
	v_cvt_pk_bf16_f32 v75, v76, v77
	s_nop 0
	v_mfma_f32_16x16x32_bf16 v[0:3], v[120:123], v[72:75], v[0:3]
	v_mfma_f32_16x16x32_bf16 v[4:7], v[124:127], v[72:75], v[4:7]
	v_mfma_f32_16x16x32_bf16 v[8:11], v[128:131], v[72:75], v[8:11]
	v_mfma_f32_16x16x32_bf16 v[12:15], v[132:135], v[72:75], v[12:15]
	v_mfma_f32_16x16x32_bf16 v[96:99], v[136:139], v[72:75], v[96:99]
	v_mfma_f32_16x16x32_bf16 v[100:103], v[144:147], v[72:75], v[100:103]
	v_mfma_f32_16x16x32_bf16 v[104:107], v[152:155], v[72:75], v[104:107]
	v_mfma_f32_16x16x32_bf16 v[108:111], v[160:163], v[72:75], v[108:111]
	v_add_co_u32_e32 v74, vcc, s72, v204
	v_lshl_add_u64 v[72:73], v[204:205], 0, s[4:5]
	s_nop 0
	v_addc_co_u32_e32 v75, vcc, 0, v205, vcc
	s_mov_b64 s[4:5], 0x14000
	global_load_dwordx4 v[168:171], v[74:75], off
	global_load_dwordx4 v[172:175], v[72:73], off offset:1024
	global_load_dwordx4 v[176:179], v[72:73], off offset:2048
	global_load_dwordx4 v[180:183], v[72:73], off offset:3072
	v_lshl_add_u64 v[72:73], v[204:205], 0, s[4:5]
	s_mov_b32 s4, 0x14000
	v_add_co_u32_e32 v74, vcc, s4, v204
	s_nop 1
	v_addc_co_u32_e32 v75, vcc, 0, v205, vcc
	global_load_dwordx4 v[164:167], v[74:75], off
	global_load_dwordx4 v[152:155], v[72:73], off offset:1024
	global_load_dwordx4 v[156:159], v[72:73], off offset:2048
	global_load_dwordx4 v[160:163], v[72:73], off offset:3072
	v_or_b32_e32 v72, 0x100, v190
	v_ashrrev_i32_e32 v73, 31, v72
	v_lshlrev_b64 v[72:73], 6, v[72:73]
	v_lshl_add_u64 v[72:73], v[202:203], 0, v[72:73]
	global_load_dwordx4 v[120:123], v[72:73], off
	v_or_b32_e32 v72, 0x110, v190
	v_ashrrev_i32_e32 v73, 31, v72
	v_lshlrev_b64 v[72:73], 6, v[72:73]
	v_lshl_add_u64 v[72:73], v[202:203], 0, v[72:73]
	global_load_dwordx4 v[124:127], v[72:73], off
	v_or_b32_e32 v72, 0x120, v190
	v_ashrrev_i32_e32 v73, 31, v72
	v_lshlrev_b64 v[72:73], 6, v[72:73]
	v_lshl_add_u64 v[72:73], v[202:203], 0, v[72:73]
	global_load_dwordx4 v[128:131], v[72:73], off
	v_or_b32_e32 v72, 0x130, v190
	v_ashrrev_i32_e32 v73, 31, v72
	v_lshlrev_b64 v[72:73], 6, v[72:73]
	v_lshl_add_u64 v[72:73], v[202:203], 0, v[72:73]
	global_load_dwordx4 v[132:135], v[72:73], off
	v_or_b32_e32 v72, 0x140, v190
	v_ashrrev_i32_e32 v73, 31, v72
	v_lshlrev_b64 v[72:73], 6, v[72:73]
	v_lshl_add_u64 v[72:73], v[202:203], 0, v[72:73]
	global_load_dwordx4 v[136:139], v[72:73], off
	v_or_b32_e32 v72, 0x150, v190
	v_ashrrev_i32_e32 v73, 31, v72
	v_lshlrev_b64 v[72:73], 6, v[72:73]
	v_lshl_add_u64 v[72:73], v[202:203], 0, v[72:73]
	global_load_dwordx4 v[140:143], v[72:73], off
	v_or_b32_e32 v72, 0x160, v190
	v_ashrrev_i32_e32 v73, 31, v72
	v_lshlrev_b64 v[72:73], 6, v[72:73]
	v_lshl_add_u64 v[72:73], v[202:203], 0, v[72:73]
	global_load_dwordx4 v[144:147], v[72:73], off
	v_or_b32_e32 v72, 0x170, v190
	v_ashrrev_i32_e32 v73, 31, v72
	v_lshlrev_b64 v[72:73], 6, v[72:73]
	v_lshl_add_u64 v[72:73], v[202:203], 0, v[72:73]
	global_load_dwordx4 v[148:151], v[72:73], off
	s_waitcnt vmcnt(15)
	v_mfma_f32_16x16x32_bf16 v[72:75], v[168:171], v[44:47], 0
	v_or_b32_e32 v204, 64, v208
	v_sub_u32_e32 v76, v191, v204
	v_cmp_lt_i32_e32 vcc, -1, v76
	s_waitcnt vmcnt(14)
	v_mfma_f32_16x16x32_bf16 v[72:75], v[172:175], v[48:51], v[72:75]
	v_cvt_f32_u32_e32 v76, v76
	v_or_b32_e32 v205, 0x41, v208
	v_or_b32_e32 v222, 0x42, v208
	s_waitcnt vmcnt(13)
	v_mfma_f32_16x16x32_bf16 v[72:75], v[176:179], v[52:55], v[72:75]
	v_mul_f32_e32 v76, v185, v76
	v_exp_f32_e32 v76, v76
	v_or_b32_e32 v239, 0x43, v208
	s_waitcnt vmcnt(12)
	v_mfma_f32_16x16x32_bf16 v[72:75], v[180:183], v[56:59], v[72:75]
	v_or_b32_e32 v244, 0x51, v208
	v_or_b32_e32 v245, 0x52, v208
	v_or_b32_e32 v246, 0x53, v208
	s_cmp_eq_u32 s70, 0
	s_nop 3
	v_mul_f32_e32 v72, v76, v72
	v_sub_u32_e32 v76, v191, v205
	v_cndmask_b32_e32 v72, 0, v72, vcc
	v_cmp_lt_i32_e32 vcc, -1, v76
	v_cvt_f32_u32_e32 v76, v76
	v_mul_f32_e32 v76, v185, v76
	v_exp_f32_e32 v76, v76
	s_nop 0
	v_mul_f32_e32 v73, v76, v73
	v_sub_u32_e32 v76, v191, v222
	v_cndmask_b32_e32 v73, 0, v73, vcc
	v_cmp_lt_i32_e32 vcc, -1, v76
	v_cvt_f32_u32_e32 v76, v76
	v_cvt_pk_bf16_f32 v240, v72, v73
	v_mul_f32_e32 v76, v185, v76
	v_exp_f32_e32 v76, v76
	s_nop 0
	v_mul_f32_e32 v74, v76, v74
	v_sub_u32_e32 v76, v191, v239
	v_cndmask_b32_e32 v74, 0, v74, vcc
	v_cmp_lt_i32_e32 vcc, -1, v76
	v_cvt_f32_u32_e32 v76, v76
	v_mul_f32_e32 v76, v185, v76
	v_exp_f32_e32 v76, v76
	s_nop 0
	v_mul_f32_e32 v75, v76, v75
	v_cndmask_b32_e32 v75, 0, v75, vcc
	v_cvt_pk_bf16_f32 v241, v74, v75
	s_waitcnt vmcnt(11)
	v_mfma_f32_16x16x32_bf16 v[72:75], v[164:167], v[44:47], 0
	v_or_b32_e32 v76, 0x50, v208
	v_sub_u32_e32 v76, v191, v76
	v_cmp_lt_i32_e32 vcc, -1, v76
	s_waitcnt vmcnt(10)
	v_mfma_f32_16x16x32_bf16 v[72:75], v[152:155], v[48:51], v[72:75]
	v_cvt_f32_u32_e32 v76, v76
	v_mul_f32_e32 v76, v185, v76
	s_waitcnt vmcnt(9)
	v_mfma_f32_16x16x32_bf16 v[72:75], v[156:159], v[52:55], v[72:75]
	v_exp_f32_e32 v76, v76
	s_waitcnt vmcnt(8)
	v_mfma_f32_16x16x32_bf16 v[72:75], v[160:163], v[56:59], v[72:75]
	s_nop 7
	v_mul_f32_e32 v72, v76, v72
	v_sub_u32_e32 v76, v191, v244
	v_cndmask_b32_e32 v72, 0, v72, vcc
	v_cmp_lt_i32_e32 vcc, -1, v76
	v_cvt_f32_u32_e32 v76, v76
	v_mul_f32_e32 v76, v185, v76
	v_exp_f32_e32 v76, v76
	s_nop 0
	v_mul_f32_e32 v73, v76, v73
	v_sub_u32_e32 v76, v191, v245
	v_cndmask_b32_e32 v73, 0, v73, vcc
	v_cmp_lt_i32_e32 vcc, -1, v76
	v_cvt_f32_u32_e32 v76, v76
	v_cvt_pk_bf16_f32 v242, v72, v73
	v_mul_f32_e32 v76, v185, v76
	v_exp_f32_e32 v76, v76
	s_nop 0
	v_mul_f32_e32 v74, v76, v74
	v_sub_u32_e32 v76, v191, v246
	v_cndmask_b32_e32 v74, 0, v74, vcc
	v_cmp_lt_i32_e32 vcc, -1, v76
	v_cvt_f32_u32_e32 v76, v76
	v_mul_f32_e32 v76, v185, v76
	v_exp_f32_e32 v76, v76
	s_nop 0
	v_mul_f32_e32 v75, v76, v75
	v_cndmask_b32_e32 v75, 0, v75, vcc
	v_cvt_pk_bf16_f32 v243, v74, v75
	s_waitcnt vmcnt(7)
	v_mfma_f32_16x16x32_bf16 v[92:95], v[120:123], v[240:243], v[16:19]
	v_mfma_f32_16x16x32_bf16 v[16:19], v[168:171], v[32:35], 0
	v_mfma_f32_16x16x32_bf16 v[16:19], v[172:175], v[20:23], v[16:19]
	v_mfma_f32_16x16x32_bf16 v[16:19], v[176:179], v[24:27], v[16:19]
	s_waitcnt vmcnt(6)
	v_mfma_f32_16x16x32_bf16 v[88:91], v[124:127], v[240:243], v[36:39]
	s_nop 2
	v_sub_u32_e32 v36, v189, v204
	v_cvt_f32_ubyte0_e32 v36, v36
	v_mul_f32_e32 v36, v185, v36
	v_mfma_f32_16x16x32_bf16 v[16:19], v[180:183], v[28:31], v[16:19]
	v_exp_f32_e32 v36, v36
	s_waitcnt vmcnt(2)
	v_mfma_f32_16x16x32_bf16 v[72:75], v[140:143], v[240:243], v[68:71]
	s_waitcnt vmcnt(1)
	v_mfma_f32_16x16x32_bf16 v[68:71], v[144:147], v[240:243], v[112:115]
	s_nop 2
	v_mul_f32_e32 v16, v36, v16
	v_sub_u32_e32 v36, v189, v205
	v_cvt_f32_ubyte0_e32 v36, v36
	v_mul_f32_e32 v36, v185, v36
	v_exp_f32_e32 v36, v36
	v_mfma_f32_16x16x32_bf16 v[84:87], v[128:131], v[240:243], v[40:43]
	v_mul_f32_e32 v17, v36, v17
	v_sub_u32_e32 v36, v189, v222
	v_cvt_f32_ubyte0_e32 v36, v36
	v_mul_f32_e32 v36, v185, v36
	v_exp_f32_e32 v36, v36
	v_cvt_pk_bf16_f32 v112, v16, v17
	v_mfma_f32_16x16x32_bf16 v[80:83], v[132:135], v[240:243], v[60:63]
	v_mul_f32_e32 v18, v36, v18
	v_sub_u32_e32 v36, v189, v239
	v_cvt_f32_ubyte0_e32 v36, v36
	v_mul_f32_e32 v36, v185, v36
	v_exp_f32_e32 v36, v36
	v_mfma_f32_16x16x32_bf16 v[76:79], v[136:139], v[240:243], v[64:67]
	v_mul_f32_e32 v19, v36, v19
	v_cvt_pk_bf16_f32 v113, v18, v19
	v_mfma_f32_16x16x32_bf16 v[16:19], v[164:167], v[32:35], 0
	v_sub_u32_e32 v36, v212, v208
	v_cmp_lt_i32_e32 vcc, -1, v36
	v_cvt_f32_u32_e32 v36, v36
	v_mfma_f32_16x16x32_bf16 v[16:19], v[152:155], v[20:23], v[16:19]
	v_mul_f32_e32 v36, v185, v36
	v_mfma_f32_16x16x32_bf16 v[16:19], v[156:159], v[24:27], v[16:19]
	v_exp_f32_e32 v36, v36
	v_mfma_f32_16x16x32_bf16 v[16:19], v[160:163], v[28:31], v[16:19]
	s_waitcnt vmcnt(0)
	v_mfma_f32_16x16x32_bf16 v[64:67], v[148:151], v[240:243], v[116:119]
	s_nop 5
	v_mul_f32_e32 v16, v36, v16
	v_sub_u32_e32 v36, v189, v244
	v_cndmask_b32_e32 v16, 0, v16, vcc
	v_cmp_lt_i32_e32 vcc, -1, v36
	v_cvt_f32_u32_e32 v36, v36
	v_mul_f32_e32 v36, v185, v36
	v_exp_f32_e32 v36, v36
	s_nop 0
	v_mul_f32_e32 v17, v36, v17
	v_sub_u32_e32 v36, v189, v245
	v_cndmask_b32_e32 v17, 0, v17, vcc
	v_cmp_lt_i32_e32 vcc, -1, v36
	v_cvt_f32_u32_e32 v36, v36
	v_cvt_pk_bf16_f32 v114, v16, v17
	v_mul_f32_e32 v36, v185, v36
	v_exp_f32_e32 v36, v36
	s_nop 0
	v_mul_f32_e32 v18, v36, v18
	v_sub_u32_e32 v36, v189, v246
	v_cndmask_b32_e32 v18, 0, v18, vcc
	v_cmp_lt_i32_e32 vcc, -1, v36
	v_cvt_f32_u32_e32 v36, v36
	v_mul_f32_e32 v36, v185, v36
	v_exp_f32_e32 v36, v36
	s_nop 0
	v_mul_f32_e32 v19, v36, v19
	v_cndmask_b32_e32 v19, 0, v19, vcc
	v_cvt_pk_bf16_f32 v115, v18, v19
	s_nop 0
	v_mfma_f32_16x16x32_bf16 v[60:63], v[120:123], v[112:115], v[0:3]
	v_mfma_f32_16x16x32_bf16 v[40:43], v[124:127], v[112:115], v[4:7]
	v_mfma_f32_16x16x32_bf16 v[36:39], v[128:131], v[112:115], v[8:11]
	v_mfma_f32_16x16x32_bf16 v[16:19], v[132:135], v[112:115], v[12:15]
	v_mfma_f32_16x16x32_bf16 v[12:15], v[136:139], v[112:115], v[96:99]
	v_mfma_f32_16x16x32_bf16 v[8:11], v[140:143], v[112:115], v[100:103]
	v_mfma_f32_16x16x32_bf16 v[4:7], v[144:147], v[112:115], v[104:107]
	v_mfma_f32_16x16x32_bf16 v[0:3], v[148:151], v[112:115], v[108:111]
	s_cbranch_scc1 .LBB0_787
	s_add_u32 s0, s0, s10
	s_addc_u32 s1, s1, s11
	v_lshl_add_u64 v[96:97], s[0:1], 0, v[186:187]
	s_mov_b64 s[0:1], 0x18000
	v_add_co_u32_e32 v100, vcc, 0x18000, v96
	v_lshl_add_u64 v[98:99], v[96:97], 0, s[0:1]
	s_nop 0
	v_addc_co_u32_e32 v101, vcc, 0, v97, vcc
	s_mov_b64 s[0:1], 0x1c000
	global_load_dwordx4 v[144:147], v[98:99], off offset:1024
	global_load_dwordx4 v[148:151], v[98:99], off offset:2048
	global_load_dwordx4 v[156:159], v[100:101], off
	global_load_dwordx4 v[152:155], v[98:99], off offset:3072
	v_lshl_add_u64 v[98:99], v[96:97], 0, s[0:1]
	v_add_co_u32_e32 v96, vcc, 0x1c000, v96
	v_or_b32_e32 v104, 0x1a0, v190
	s_nop 0
	v_addc_co_u32_e32 v97, vcc, 0, v97, vcc
	global_load_dwordx4 v[128:131], v[98:99], off offset:1024
	global_load_dwordx4 v[132:135], v[98:99], off offset:2048
	global_load_dwordx4 v[140:143], v[96:97], off
	global_load_dwordx4 v[136:139], v[98:99], off offset:3072
	v_or_b32_e32 v96, 0x180, v190
	v_or_b32_e32 v98, 0x190, v190
	v_or_b32_e32 v106, 0x1b0, v190
	v_or_b32_e32 v112, 0x1c0, v190
	v_or_b32_e32 v114, 0x1d0, v190
	v_or_b32_e32 v120, 0x1e0, v190
	v_or_b32_e32 v122, 0x1f0, v190
	v_ashrrev_i32_e32 v97, 31, v96
	v_ashrrev_i32_e32 v99, 31, v98
	v_ashrrev_i32_e32 v105, 31, v104
	v_ashrrev_i32_e32 v107, 31, v106
	v_ashrrev_i32_e32 v113, 31, v112
	v_ashrrev_i32_e32 v115, 31, v114
	v_ashrrev_i32_e32 v121, 31, v120
	v_ashrrev_i32_e32 v123, 31, v122
	v_lshlrev_b64 v[96:97], 6, v[96:97]
	v_lshlrev_b64 v[98:99], 6, v[98:99]
	v_lshlrev_b64 v[104:105], 6, v[104:105]
	v_lshlrev_b64 v[106:107], 6, v[106:107]
	v_lshlrev_b64 v[112:113], 6, v[112:113]
	v_lshlrev_b64 v[114:115], 6, v[114:115]
	v_lshlrev_b64 v[120:121], 6, v[120:121]
	v_lshlrev_b64 v[122:123], 6, v[122:123]
	v_lshl_add_u64 v[96:97], v[202:203], 0, v[96:97]
	v_lshl_add_u64 v[100:101], v[202:203], 0, v[98:99]
	v_lshl_add_u64 v[104:105], v[202:203], 0, v[104:105]
	v_lshl_add_u64 v[108:109], v[202:203], 0, v[106:107]
	v_lshl_add_u64 v[112:113], v[202:203], 0, v[112:113]
	v_lshl_add_u64 v[116:117], v[202:203], 0, v[114:115]
	v_lshl_add_u64 v[120:121], v[202:203], 0, v[120:121]
	v_lshl_add_u64 v[124:125], v[202:203], 0, v[122:123]
	global_load_dwordx4 v[96:99], v[96:97], off
	s_nop 0
	global_load_dwordx4 v[100:103], v[100:101], off
	s_nop 0
	global_load_dwordx4 v[104:107], v[104:105], off
	s_nop 0
	global_load_dwordx4 v[108:111], v[108:109], off
	s_nop 0
	global_load_dwordx4 v[112:115], v[112:113], off
	s_nop 0
	global_load_dwordx4 v[116:119], v[116:117], off
	s_nop 0
	global_load_dwordx4 v[120:123], v[120:121], off
	s_nop 0
	global_load_dwordx4 v[124:127], v[124:125], off
	s_waitcnt vmcnt(13)
	v_mfma_f32_16x16x32_bf16 v[44:47], v[156:159], v[44:47], 0
	v_mfma_f32_16x16x32_bf16 v[44:47], v[144:147], v[48:51], v[44:47]
	v_or_b32_e32 v49, 0x61, v208
	v_sub_u32_e32 v50, v238, v49
	v_cmp_lt_i32_e64 s[40:41], -1, v50
	v_cvt_f32_u32_e32 v50, v50
	v_mfma_f32_16x16x32_bf16 v[44:47], v[148:151], v[52:55], v[44:47]
	v_sub_u32_e32 v48, v206, v208
	v_cmp_lt_i32_e32 vcc, -1, v48
	v_mul_f32_e32 v50, v185, v50
	s_waitcnt vmcnt(12)
	v_mfma_f32_16x16x32_bf16 v[44:47], v[152:155], v[56:59], v[44:47]
	v_exp_f32_e32 v50, v50
	v_cvt_f32_u32_e32 v48, v48
	v_sub_u32_e32 v49, v223, v49
	v_cvt_f32_ubyte0_e32 v49, v49
	v_mul_f32_e32 v49, v185, v49
	s_nop 2
	v_mul_f32_e32 v45, v50, v45
	v_or_b32_e32 v50, 0x62, v208
	v_sub_u32_e32 v51, v238, v50
	v_cndmask_b32_e64 v45, 0, v45, s[40:41]
	v_cmp_lt_i32_e64 s[40:41], -1, v51
	v_cvt_f32_u32_e32 v51, v51
	v_mul_f32_e32 v48, v185, v48
	v_exp_f32_e32 v48, v48
	v_exp_f32_e32 v49, v49
	v_mul_f32_e32 v51, v185, v51
	v_exp_f32_e32 v51, v51
	v_mul_f32_e32 v44, v48, v44
	v_cndmask_b32_e32 v44, 0, v44, vcc
	v_cvt_pk_bf16_f32 v44, v44, v45
	v_mul_f32_e32 v46, v51, v46
	v_or_b32_e32 v51, 0x63, v208
	v_sub_u32_e32 v52, v238, v51
	v_cndmask_b32_e64 v46, 0, v46, s[40:41]
	v_cmp_lt_i32_e64 s[40:41], -1, v52
	v_cvt_f32_u32_e32 v52, v52
	v_mul_f32_e32 v52, v185, v52
	v_exp_f32_e32 v52, v52
	s_nop 0
	v_mul_f32_e32 v47, v52, v47
	v_cndmask_b32_e64 v47, 0, v47, s[40:41]
	v_cvt_pk_bf16_f32 v45, v46, v47
	v_cvt_pk_bf16_f32 v46, v197, v197
	v_cvt_pk_bf16_f32 v47, v197, v197
	v_sub_u32_e32 v52, v210, v208
	v_cvt_f32_ubyte0_e32 v52, v52
	s_waitcnt vmcnt(7)
	v_mfma_f32_16x16x32_bf16 v[92:95], v[96:99], v[44:47], v[92:95]
	v_mul_f32_e32 v52, v185, v52
	v_exp_f32_e32 v52, v52
	s_waitcnt vmcnt(6)
	v_mfma_f32_16x16x32_bf16 v[88:91], v[100:103], v[44:47], v[88:91]
	s_waitcnt vmcnt(5)
	v_mfma_f32_16x16x32_bf16 v[84:87], v[104:107], v[44:47], v[84:87]
	s_waitcnt vmcnt(4)
	v_mfma_f32_16x16x32_bf16 v[80:83], v[108:111], v[44:47], v[80:83]
	s_waitcnt vmcnt(3)
	v_mfma_f32_16x16x32_bf16 v[76:79], v[112:115], v[44:47], v[76:79]
	s_waitcnt vmcnt(2)
	v_mfma_f32_16x16x32_bf16 v[72:75], v[116:119], v[44:47], v[72:75]
	s_waitcnt vmcnt(1)
	v_mfma_f32_16x16x32_bf16 v[68:71], v[120:123], v[44:47], v[68:71]
	s_waitcnt vmcnt(0)
	v_mfma_f32_16x16x32_bf16 v[64:67], v[124:127], v[44:47], v[64:67]
	v_mfma_f32_16x16x32_bf16 v[44:47], v[156:159], v[32:35], 0
	v_mfma_f32_16x16x32_bf16 v[32:35], v[140:143], v[32:35], 0
	v_mfma_f32_16x16x32_bf16 v[44:47], v[144:147], v[20:23], v[44:47]
	v_mfma_f32_16x16x32_bf16 v[20:23], v[128:131], v[20:23], v[32:35]
	v_mfma_f32_16x16x32_bf16 v[20:23], v[132:135], v[24:27], v[20:23]
	v_mfma_f32_16x16x32_bf16 v[20:23], v[136:139], v[28:31], v[20:23]
	v_mfma_f32_16x16x32_bf16 v[44:47], v[148:151], v[24:27], v[44:47]
	v_or_b32_e32 v24, 0x71, v208
	s_nop 5
	v_mul_f32_e32 v20, v48, v20
	v_sub_u32_e32 v24, v223, v24
	v_cndmask_b32_e32 v20, 0, v20, vcc
	v_cmp_lt_i32_e32 vcc, -1, v24
	v_cvt_f32_u32_e32 v24, v24
	v_mfma_f32_16x16x32_bf16 v[44:47], v[152:155], v[28:31], v[44:47]
	v_mul_f32_e32 v24, v185, v24
	v_exp_f32_e32 v24, v24
	s_nop 0
	v_mul_f32_e32 v21, v24, v21
	v_or_b32_e32 v24, 0x72, v208
	v_sub_u32_e32 v24, v223, v24
	v_cndmask_b32_e32 v21, 0, v21, vcc
	v_cmp_lt_i32_e32 vcc, -1, v24
	v_cvt_f32_u32_e32 v24, v24
	v_mul_f32_e32 v45, v49, v45
	v_sub_u32_e32 v49, v223, v50
	v_cvt_f32_ubyte0_e32 v49, v49
	v_mul_f32_e32 v24, v185, v24
	v_exp_f32_e32 v24, v24
	v_mul_f32_e32 v49, v185, v49
	v_exp_f32_e32 v49, v49
	v_mul_f32_e32 v44, v52, v44
	v_mul_f32_e32 v22, v24, v22
	v_or_b32_e32 v24, 0x73, v208
	v_sub_u32_e32 v24, v223, v24
	v_cndmask_b32_e32 v22, 0, v22, vcc
	v_cmp_lt_i32_e32 vcc, -1, v24
	v_cvt_f32_u32_e32 v24, v24
	v_mul_f32_e32 v46, v49, v46
	v_sub_u32_e32 v49, v223, v51
	v_cvt_f32_ubyte0_e32 v49, v49
	v_mul_f32_e32 v49, v185, v49
	v_mul_f32_e32 v24, v185, v24
	v_exp_f32_e32 v49, v49
	v_exp_f32_e32 v24, v24
	v_cvt_pk_bf16_f32 v44, v44, v45
	v_mul_f32_e32 v47, v49, v47
	v_mul_f32_e32 v23, v24, v23
	v_cvt_pk_bf16_f32 v45, v46, v47
	v_cndmask_b32_e32 v23, 0, v23, vcc
	v_cvt_pk_bf16_f32 v46, v20, v21
	v_cvt_pk_bf16_f32 v47, v22, v23
	s_nop 0
	v_mfma_f32_16x16x32_bf16 v[60:63], v[96:99], v[44:47], v[60:63]
	v_mfma_f32_16x16x32_bf16 v[40:43], v[100:103], v[44:47], v[40:43]
	v_mfma_f32_16x16x32_bf16 v[36:39], v[104:107], v[44:47], v[36:39]
	v_mfma_f32_16x16x32_bf16 v[16:19], v[108:111], v[44:47], v[16:19]
	v_mfma_f32_16x16x32_bf16 v[12:15], v[112:115], v[44:47], v[12:15]
	v_mfma_f32_16x16x32_bf16 v[8:11], v[116:119], v[44:47], v[8:11]
	v_mfma_f32_16x16x32_bf16 v[4:7], v[120:123], v[44:47], v[4:7]
	v_mfma_f32_16x16x32_bf16 v[0:3], v[124:127], v[44:47], v[0:3]
